# accumulator-stationary MFMA order plus all s_setprio flips removed from the GEMM K-loops
# speedup vs baseline: 1.0151x; 1.0017x over previous
.LBB0_101:
	ds_read_b128 v[154:157], v151
	ds_read_b128 v[158:161], v151 offset:1024
	ds_read_b128 v[162:165], v151 offset:2048
	ds_read_b128 v[166:169], v151 offset:3072
	ds_read_b128 v[170:173], v152
	ds_read_b128 v[174:177], v152 offset:1024
	ds_read_b128 v[188:191], v152 offset:2048
	ds_read_b128 v[192:195], v152 offset:3072
	s_add_u32 s40, s36, s38
	s_addc_u32 s41, s37, s39
	s_add_u32 s44, s40, 0x100
	s_addc_u32 s45, s41, 0
	s_add_u32 s42, s66, s38
	s_addc_u32 s43, s67, s39
	s_add_u32 s40, s40, 0x180
	s_addc_u32 s41, s41, 0
	s_cmpk_eq_i32 s38, 0x1f00
	s_cselect_b32 s41, s65, s41
	s_cselect_b32 s40, s64, s40
	s_cselect_b32 s43, s35, s43
	s_cselect_b32 s42, s34, s42
	s_cselect_b32 s45, s23, s45
	s_cselect_b32 s44, s22, s44
	s_mov_b32 m0, s57
	v_lshl_add_u64 v[178:179], v[146:147], 0, s[38:39]
	ds_read_b128 v[196:199], v153
	ds_read_b128 v[200:203], v153 offset:1024
	ds_read_b128 v[204:207], v153 offset:2048
	ds_read_b128 v[208:211], v153 offset:3072
	ds_read_b128 v[214:217], v153 offset:4096
	ds_read_b128 v[218:221], v153 offset:5120
	ds_read_b128 v[222:225], v153 offset:6144
	ds_read_b128 v[226:229], v153 offset:7168
	global_load_lds_dwordx4 v[178:179], off
	v_lshl_add_u64 v[178:179], v[148:149], 0, s[38:39]
	s_add_i32 m0, s47, 0xe000
	s_nop 0
	global_load_lds_dwordx4 v[178:179], off
	s_waitcnt vmcnt(8)
	s_waitcnt lgkmcnt(0)
	s_barrier
	s_waitcnt lgkmcnt(0)
	v_mfma_f32_16x16x32_bf16 v[126:129], v[154:157], v[196:199], v[126:129]
	v_mfma_f32_16x16x32_bf16 v[126:129], v[158:161], v[200:203], v[126:129]
	v_mfma_f32_16x16x32_bf16 v[122:125], v[162:165], v[196:199], v[122:125]
	v_mfma_f32_16x16x32_bf16 v[122:125], v[166:169], v[200:203], v[122:125]
	v_mfma_f32_16x16x32_bf16 v[118:121], v[154:157], v[204:207], v[118:121]
	v_mfma_f32_16x16x32_bf16 v[118:121], v[158:161], v[208:211], v[118:121]
	v_mfma_f32_16x16x32_bf16 v[110:113], v[162:165], v[204:207], v[110:113]
	v_mfma_f32_16x16x32_bf16 v[110:113], v[166:169], v[208:211], v[110:113]
	v_mfma_f32_16x16x32_bf16 v[102:105], v[154:157], v[214:217], v[102:105]
	v_mfma_f32_16x16x32_bf16 v[102:105], v[158:161], v[218:221], v[102:105]
	v_mfma_f32_16x16x32_bf16 v[94:97], v[162:165], v[214:217], v[94:97]
	v_mfma_f32_16x16x32_bf16 v[94:97], v[166:169], v[218:221], v[94:97]
	v_mfma_f32_16x16x32_bf16 v[86:89], v[154:157], v[222:225], v[86:89]
	v_mfma_f32_16x16x32_bf16 v[86:89], v[158:161], v[226:229], v[86:89]
	v_mfma_f32_16x16x32_bf16 v[78:81], v[162:165], v[222:225], v[78:81]
	v_mfma_f32_16x16x32_bf16 v[78:81], v[166:169], v[226:229], v[78:81]
	v_mfma_f32_16x16x32_bf16 v[114:117], v[170:173], v[196:199], v[114:117]
	v_mfma_f32_16x16x32_bf16 v[114:117], v[174:177], v[200:203], v[114:117]
	v_mfma_f32_16x16x32_bf16 v[106:109], v[188:191], v[196:199], v[106:109]
	v_mfma_f32_16x16x32_bf16 v[106:109], v[192:195], v[200:203], v[106:109]
	v_mfma_f32_16x16x32_bf16 v[98:101], v[170:173], v[204:207], v[98:101]
	v_mfma_f32_16x16x32_bf16 v[98:101], v[174:177], v[208:211], v[98:101]
	v_mfma_f32_16x16x32_bf16 v[90:93], v[188:191], v[204:207], v[90:93]
	v_mfma_f32_16x16x32_bf16 v[90:93], v[192:195], v[208:211], v[90:93]
	v_mfma_f32_16x16x32_bf16 v[82:85], v[170:173], v[214:217], v[82:85]
	v_mfma_f32_16x16x32_bf16 v[82:85], v[174:177], v[218:221], v[82:85]
	v_mfma_f32_16x16x32_bf16 v[74:77], v[188:191], v[214:217], v[74:77]
	v_mfma_f32_16x16x32_bf16 v[74:77], v[192:195], v[218:221], v[74:77]
	v_mfma_f32_16x16x32_bf16 v[70:73], v[170:173], v[222:225], v[70:73]
	v_mfma_f32_16x16x32_bf16 v[70:73], v[174:177], v[226:229], v[70:73]
	v_mfma_f32_16x16x32_bf16 v[66:69], v[188:191], v[222:225], v[66:69]
	v_mfma_f32_16x16x32_bf16 v[66:69], v[192:195], v[226:229], v[66:69]
	s_barrier
	s_add_i32 s69, s54, s3
	v_lshl_add_u64 v[178:179], s[42:43], 0, v[136:137]
	s_mov_b32 m0, s69
	ds_read_b128 v[196:199], v153 offset:16384
	ds_read_b128 v[200:203], v153 offset:17408
	ds_read_b128 v[204:207], v153 offset:18432
	ds_read_b128 v[208:211], v153 offset:19456
	ds_read_b128 v[214:217], v153 offset:20480
	ds_read_b128 v[218:221], v153 offset:21504
	ds_read_b128 v[222:225], v153 offset:22528
	ds_read_b128 v[226:229], v153 offset:23552
	global_load_lds_dwordx4 v[178:179], off
	s_add_i32 m0, s69, 0x2000
	s_add_u32 s70, s42, 0x108000
	v_lshl_add_u64 v[230:231], s[42:43], 0, v[140:141]
	s_addc_u32 s71, s43, 0
	s_add_i32 s69, s55, s3
	global_load_lds_dwordx4 v[230:231], off
	v_lshl_add_u64 v[232:233], s[70:71], 0, v[136:137]
	s_mov_b32 m0, s69
	s_nop 0
	global_load_lds_dwordx4 v[232:233], off
	v_lshl_add_u64 v[232:233], s[70:71], 0, v[140:141]
	s_add_i32 m0, s69, 0x2000
	s_nop 0
	global_load_lds_dwordx4 v[232:233], off
	v_lshl_add_u64 v[232:233], s[44:45], 0, v[134:135]
	s_mov_b32 m0, s47
	s_nop 0
	global_load_lds_dwordx4 v[232:233], off
	v_lshl_add_u64 v[232:233], s[44:45], 0, v[138:139]
	s_mov_b32 m0, s48
	s_nop 0
	global_load_lds_dwordx4 v[232:233], off
	s_waitcnt vmcnt(8)
	s_waitcnt lgkmcnt(0)
	s_barrier
	s_waitcnt lgkmcnt(0)
	v_mfma_f32_16x16x32_bf16 v[62:65], v[154:157], v[196:199], v[62:65]
	v_mfma_f32_16x16x32_bf16 v[62:65], v[158:161], v[200:203], v[62:65]
	v_mfma_f32_16x16x32_bf16 v[58:61], v[162:165], v[196:199], v[58:61]
	v_mfma_f32_16x16x32_bf16 v[58:61], v[166:169], v[200:203], v[58:61]
	v_mfma_f32_16x16x32_bf16 v[54:57], v[154:157], v[204:207], v[54:57]
	v_mfma_f32_16x16x32_bf16 v[54:57], v[158:161], v[208:211], v[54:57]
	v_mfma_f32_16x16x32_bf16 v[46:49], v[162:165], v[204:207], v[46:49]
	v_mfma_f32_16x16x32_bf16 v[46:49], v[166:169], v[208:211], v[46:49]
	v_mfma_f32_16x16x32_bf16 v[38:41], v[154:157], v[214:217], v[38:41]
	v_mfma_f32_16x16x32_bf16 v[38:41], v[158:161], v[218:221], v[38:41]
	v_mfma_f32_16x16x32_bf16 v[30:33], v[162:165], v[214:217], v[30:33]
	v_mfma_f32_16x16x32_bf16 v[30:33], v[166:169], v[218:221], v[30:33]
	v_mfma_f32_16x16x32_bf16 v[22:25], v[154:157], v[222:225], v[22:25]
	v_mfma_f32_16x16x32_bf16 v[22:25], v[158:161], v[226:229], v[22:25]
	v_mfma_f32_16x16x32_bf16 v[14:17], v[162:165], v[222:225], v[14:17]
	v_mfma_f32_16x16x32_bf16 v[14:17], v[166:169], v[226:229], v[14:17]
	v_mfma_f32_16x16x32_bf16 v[50:53], v[170:173], v[196:199], v[50:53]
	v_mfma_f32_16x16x32_bf16 v[50:53], v[174:177], v[200:203], v[50:53]
	v_mfma_f32_16x16x32_bf16 v[42:45], v[188:191], v[196:199], v[42:45]
	v_mfma_f32_16x16x32_bf16 v[42:45], v[192:195], v[200:203], v[42:45]
	v_mfma_f32_16x16x32_bf16 v[34:37], v[170:173], v[204:207], v[34:37]
	v_mfma_f32_16x16x32_bf16 v[34:37], v[174:177], v[208:211], v[34:37]
	v_mfma_f32_16x16x32_bf16 v[26:29], v[188:191], v[204:207], v[26:29]
	v_mfma_f32_16x16x32_bf16 v[26:29], v[192:195], v[208:211], v[26:29]
	v_mfma_f32_16x16x32_bf16 v[18:21], v[170:173], v[214:217], v[18:21]
	v_mfma_f32_16x16x32_bf16 v[18:21], v[174:177], v[218:221], v[18:21]
	v_mfma_f32_16x16x32_bf16 v[10:13], v[188:191], v[214:217], v[10:13]
	v_mfma_f32_16x16x32_bf16 v[10:13], v[192:195], v[218:221], v[10:13]
	v_mfma_f32_16x16x32_bf16 v[6:9], v[170:173], v[222:225], v[6:9]
	v_mfma_f32_16x16x32_bf16 v[6:9], v[174:177], v[226:229], v[6:9]
	v_mfma_f32_16x16x32_bf16 v[2:5], v[188:191], v[222:225], v[2:5]
	v_mfma_f32_16x16x32_bf16 v[2:5], v[192:195], v[226:229], v[2:5]
	s_barrier
	s_add_i32 s69, 0, 0x18000
	s_add_i32 s70, 0, 0x1c000
	v_add_u32_e32 v166, s69, v133
	v_add_u32_e32 v187, s70, v133
	ds_read_b128 v[154:157], v166
	ds_read_b128 v[158:161], v166 offset:1024
	ds_read_b128 v[162:165], v166 offset:2048
	ds_read_b128 v[166:169], v166 offset:3072
	ds_read_b128 v[170:173], v187
	ds_read_b128 v[174:177], v187 offset:1024
	ds_read_b128 v[188:191], v187 offset:2048
	ds_read_b128 v[192:195], v187 offset:3072
	s_add_u32 s44, s44, 0x108000
	s_addc_u32 s45, s45, 0
	s_mov_b32 m0, s49
	v_lshl_add_u64 v[232:233], s[44:45], 0, v[134:135]
	ds_read_b128 v[196:199], v153 offset:32768
	ds_read_b128 v[200:203], v153 offset:33792
	ds_read_b128 v[204:207], v153 offset:34816
	ds_read_b128 v[208:211], v153 offset:35840
	ds_read_b128 v[214:217], v153 offset:36864
	ds_read_b128 v[218:221], v153 offset:37888
	ds_read_b128 v[222:225], v153 offset:38912
	ds_read_b128 v[226:229], v153 offset:39936
	global_load_lds_dwordx4 v[232:233], off
	v_lshl_add_u64 v[232:233], s[44:45], 0, v[138:139]
	s_mov_b32 m0, s50
	s_nop 0
	global_load_lds_dwordx4 v[232:233], off
	s_waitcnt vmcnt(8)
	s_waitcnt lgkmcnt(0)
	s_barrier
	s_waitcnt lgkmcnt(0)
	v_mfma_f32_16x16x32_bf16 v[126:129], v[154:157], v[196:199], v[126:129]
	v_mfma_f32_16x16x32_bf16 v[126:129], v[158:161], v[200:203], v[126:129]
	v_mfma_f32_16x16x32_bf16 v[122:125], v[162:165], v[196:199], v[122:125]
	v_mfma_f32_16x16x32_bf16 v[122:125], v[166:169], v[200:203], v[122:125]
	v_mfma_f32_16x16x32_bf16 v[118:121], v[154:157], v[204:207], v[118:121]
	v_mfma_f32_16x16x32_bf16 v[118:121], v[158:161], v[208:211], v[118:121]
	v_mfma_f32_16x16x32_bf16 v[110:113], v[162:165], v[204:207], v[110:113]
	v_mfma_f32_16x16x32_bf16 v[110:113], v[166:169], v[208:211], v[110:113]
	v_mfma_f32_16x16x32_bf16 v[102:105], v[154:157], v[214:217], v[102:105]
	v_mfma_f32_16x16x32_bf16 v[102:105], v[158:161], v[218:221], v[102:105]
	v_mfma_f32_16x16x32_bf16 v[94:97], v[162:165], v[214:217], v[94:97]
	v_mfma_f32_16x16x32_bf16 v[94:97], v[166:169], v[218:221], v[94:97]
	v_mfma_f32_16x16x32_bf16 v[86:89], v[154:157], v[222:225], v[86:89]
	v_mfma_f32_16x16x32_bf16 v[86:89], v[158:161], v[226:229], v[86:89]
	v_mfma_f32_16x16x32_bf16 v[78:81], v[162:165], v[222:225], v[78:81]
	v_mfma_f32_16x16x32_bf16 v[78:81], v[166:169], v[226:229], v[78:81]
	v_mfma_f32_16x16x32_bf16 v[114:117], v[170:173], v[196:199], v[114:117]
	v_mfma_f32_16x16x32_bf16 v[114:117], v[174:177], v[200:203], v[114:117]
	v_mfma_f32_16x16x32_bf16 v[106:109], v[188:191], v[196:199], v[106:109]
	v_mfma_f32_16x16x32_bf16 v[106:109], v[192:195], v[200:203], v[106:109]
	v_mfma_f32_16x16x32_bf16 v[98:101], v[170:173], v[204:207], v[98:101]
	v_mfma_f32_16x16x32_bf16 v[98:101], v[174:177], v[208:211], v[98:101]
	v_mfma_f32_16x16x32_bf16 v[90:93], v[188:191], v[204:207], v[90:93]
	v_mfma_f32_16x16x32_bf16 v[90:93], v[192:195], v[208:211], v[90:93]
	v_mfma_f32_16x16x32_bf16 v[82:85], v[170:173], v[214:217], v[82:85]
	v_mfma_f32_16x16x32_bf16 v[82:85], v[174:177], v[218:221], v[82:85]
	v_mfma_f32_16x16x32_bf16 v[74:77], v[188:191], v[214:217], v[74:77]
	v_mfma_f32_16x16x32_bf16 v[74:77], v[192:195], v[218:221], v[74:77]
	v_mfma_f32_16x16x32_bf16 v[70:73], v[170:173], v[222:225], v[70:73]
	v_mfma_f32_16x16x32_bf16 v[70:73], v[174:177], v[226:229], v[70:73]
	v_mfma_f32_16x16x32_bf16 v[66:69], v[188:191], v[222:225], v[66:69]
	v_mfma_f32_16x16x32_bf16 v[66:69], v[192:195], v[226:229], v[66:69]
	s_barrier
	s_add_i32 s44, s69, s3
	v_lshl_add_u64 v[178:179], v[178:179], 0, s[12:13]
	s_mov_b32 m0, s44
	ds_read_b128 v[196:199], v153 offset:49152
	ds_read_b128 v[200:203], v153 offset:50176
	ds_read_b128 v[204:207], v153 offset:51200
	ds_read_b128 v[208:211], v153 offset:52224
	ds_read_b128 v[214:217], v153 offset:53248
	ds_read_b128 v[218:221], v153 offset:54272
	ds_read_b128 v[222:225], v153 offset:55296
	ds_read_b128 v[226:229], v153 offset:56320
	global_load_lds_dwordx4 v[178:179], off
	s_add_i32 m0, s44, 0x2000
	s_add_u32 s42, s42, 0x108080
	v_lshl_add_u64 v[178:179], v[230:231], 0, s[12:13]
	s_addc_u32 s43, s43, 0
	s_add_i32 s44, s70, s3
	global_load_lds_dwordx4 v[178:179], off
	v_lshl_add_u64 v[178:179], s[42:43], 0, v[136:137]
	s_mov_b32 m0, s44
	s_nop 0
	global_load_lds_dwordx4 v[178:179], off
	v_lshl_add_u64 v[178:179], s[42:43], 0, v[140:141]
	s_add_i32 m0, s44, 0x2000
	s_nop 0
	global_load_lds_dwordx4 v[178:179], off
	v_lshl_add_u64 v[178:179], s[40:41], 0, v[134:135]
	s_mov_b32 m0, s52
	s_nop 0
	global_load_lds_dwordx4 v[178:179], off
	v_lshl_add_u64 v[178:179], s[40:41], 0, v[138:139]
	s_mov_b32 m0, s53
	s_nop 0
	global_load_lds_dwordx4 v[178:179], off
	s_waitcnt vmcnt(8)
	s_waitcnt lgkmcnt(0)
	s_barrier
	s_waitcnt lgkmcnt(0)
	v_mfma_f32_16x16x32_bf16 v[62:65], v[154:157], v[196:199], v[62:65]
	v_mfma_f32_16x16x32_bf16 v[62:65], v[158:161], v[200:203], v[62:65]
	v_mfma_f32_16x16x32_bf16 v[58:61], v[162:165], v[196:199], v[58:61]
	v_mfma_f32_16x16x32_bf16 v[58:61], v[166:169], v[200:203], v[58:61]
	v_mfma_f32_16x16x32_bf16 v[54:57], v[154:157], v[204:207], v[54:57]
	v_mfma_f32_16x16x32_bf16 v[54:57], v[158:161], v[208:211], v[54:57]
	v_mfma_f32_16x16x32_bf16 v[46:49], v[162:165], v[204:207], v[46:49]
	v_mfma_f32_16x16x32_bf16 v[46:49], v[166:169], v[208:211], v[46:49]
	v_mfma_f32_16x16x32_bf16 v[38:41], v[154:157], v[214:217], v[38:41]
	v_mfma_f32_16x16x32_bf16 v[38:41], v[158:161], v[218:221], v[38:41]
	v_mfma_f32_16x16x32_bf16 v[30:33], v[162:165], v[214:217], v[30:33]
	v_mfma_f32_16x16x32_bf16 v[30:33], v[166:169], v[218:221], v[30:33]
	v_mfma_f32_16x16x32_bf16 v[22:25], v[154:157], v[222:225], v[22:25]
	v_mfma_f32_16x16x32_bf16 v[22:25], v[158:161], v[226:229], v[22:25]
	v_mfma_f32_16x16x32_bf16 v[14:17], v[162:165], v[222:225], v[14:17]
	v_mfma_f32_16x16x32_bf16 v[14:17], v[166:169], v[226:229], v[14:17]
	v_mfma_f32_16x16x32_bf16 v[50:53], v[170:173], v[196:199], v[50:53]
	v_mfma_f32_16x16x32_bf16 v[50:53], v[174:177], v[200:203], v[50:53]
	v_mfma_f32_16x16x32_bf16 v[42:45], v[188:191], v[196:199], v[42:45]
	v_mfma_f32_16x16x32_bf16 v[42:45], v[192:195], v[200:203], v[42:45]
	v_mfma_f32_16x16x32_bf16 v[34:37], v[170:173], v[204:207], v[34:37]
	v_mfma_f32_16x16x32_bf16 v[34:37], v[174:177], v[208:211], v[34:37]
	v_mfma_f32_16x16x32_bf16 v[26:29], v[188:191], v[204:207], v[26:29]
	v_mfma_f32_16x16x32_bf16 v[26:29], v[192:195], v[208:211], v[26:29]
	v_mfma_f32_16x16x32_bf16 v[18:21], v[170:173], v[214:217], v[18:21]
	v_mfma_f32_16x16x32_bf16 v[18:21], v[174:177], v[218:221], v[18:21]
	v_mfma_f32_16x16x32_bf16 v[10:13], v[188:191], v[214:217], v[10:13]
	v_mfma_f32_16x16x32_bf16 v[10:13], v[192:195], v[218:221], v[10:13]
	v_mfma_f32_16x16x32_bf16 v[6:9], v[170:173], v[222:225], v[6:9]
	v_mfma_f32_16x16x32_bf16 v[6:9], v[174:177], v[226:229], v[6:9]
	v_mfma_f32_16x16x32_bf16 v[2:5], v[188:191], v[222:225], v[2:5]
	v_mfma_f32_16x16x32_bf16 v[2:5], v[192:195], v[226:229], v[2:5]
	s_barrier
	s_add_i32 s68, s68, 2
	s_add_u32 s38, s38, 0x100
	s_addc_u32 s39, s39, 0
	s_cmp_gt_u32 s68, 61
	s_cbranch_scc0 .LBB0_101
	s_and_b64 vcc, exec, s[20:21]
	s_cbranch_vccz .LBB0_104
	s_barrier

.LBB0_235:
	ds_read_b128 v[156:159], v150
	ds_read_b128 v[160:163], v150 offset:1024
	ds_read_b128 v[164:167], v150 offset:2048
	ds_read_b128 v[168:171], v150 offset:3072
	ds_read_b128 v[172:175], v151
	ds_read_b128 v[176:179], v151 offset:1024
	ds_read_b128 v[180:183], v151 offset:2048
	ds_read_b128 v[184:187], v151 offset:3072
	s_add_u32 s36, s4, s34
	s_addc_u32 s37, s5, s35
	s_add_u32 s40, s36, 0x100
	s_addc_u32 s41, s37, 0
	s_add_u32 s38, s62, s34
	s_addc_u32 s39, s63, s35
	s_add_u32 s36, s36, 0x180
	s_addc_u32 s37, s37, 0
	s_cmpk_eq_i32 s34, 0x1f00
	s_cselect_b32 s37, s61, s37
	s_cselect_b32 s36, s60, s36
	s_cselect_b32 s39, s31, s39
	s_cselect_b32 s38, s30, s38
	s_cselect_b32 s41, s23, s41
	s_cselect_b32 s40, s22, s40
	s_mov_b32 m0, s46
	v_lshl_add_u64 v[222:223], v[146:147], 0, s[34:35]
	ds_read_b128 v[188:191], v152
	ds_read_b128 v[192:195], v152 offset:1024
	ds_read_b128 v[196:199], v152 offset:2048
	ds_read_b128 v[200:203], v152 offset:3072
	ds_read_b128 v[204:207], v152 offset:4096
	ds_read_b128 v[208:211], v152 offset:5120
	ds_read_b128 v[214:217], v152 offset:6144
	ds_read_b128 v[218:221], v152 offset:7168
	global_load_lds_dwordx4 v[222:223], off
	v_lshl_add_u64 v[222:223], v[148:149], 0, s[34:35]
	s_mov_b32 m0, s47
	s_nop 0
	global_load_lds_dwordx4 v[222:223], off
	s_waitcnt vmcnt(8)
	s_waitcnt lgkmcnt(0)
	s_barrier
	s_waitcnt lgkmcnt(0)
	v_mfma_f32_16x16x32_bf16 v[126:129], v[156:159], v[188:191], v[126:129]
	v_mfma_f32_16x16x32_bf16 v[126:129], v[160:163], v[192:195], v[126:129]
	v_mfma_f32_16x16x32_bf16 v[122:125], v[164:167], v[188:191], v[122:125]
	v_mfma_f32_16x16x32_bf16 v[122:125], v[168:171], v[192:195], v[122:125]
	v_mfma_f32_16x16x32_bf16 v[110:113], v[156:159], v[196:199], v[110:113]
	v_mfma_f32_16x16x32_bf16 v[110:113], v[160:163], v[200:203], v[110:113]
	v_mfma_f32_16x16x32_bf16 v[106:109], v[164:167], v[196:199], v[106:109]
	v_mfma_f32_16x16x32_bf16 v[106:109], v[168:171], v[200:203], v[106:109]
	v_mfma_f32_16x16x32_bf16 v[94:97], v[156:159], v[204:207], v[94:97]
	v_mfma_f32_16x16x32_bf16 v[94:97], v[160:163], v[208:211], v[94:97]
	v_mfma_f32_16x16x32_bf16 v[90:93], v[164:167], v[204:207], v[90:93]
	v_mfma_f32_16x16x32_bf16 v[90:93], v[168:171], v[208:211], v[90:93]
	v_mfma_f32_16x16x32_bf16 v[78:81], v[156:159], v[214:217], v[78:81]
	v_mfma_f32_16x16x32_bf16 v[78:81], v[160:163], v[218:221], v[78:81]
	v_mfma_f32_16x16x32_bf16 v[74:77], v[164:167], v[214:217], v[74:77]
	v_mfma_f32_16x16x32_bf16 v[74:77], v[168:171], v[218:221], v[74:77]
	v_mfma_f32_16x16x32_bf16 v[118:121], v[172:175], v[188:191], v[118:121]
	v_mfma_f32_16x16x32_bf16 v[118:121], v[176:179], v[192:195], v[118:121]
	v_mfma_f32_16x16x32_bf16 v[114:117], v[180:183], v[188:191], v[114:117]
	v_mfma_f32_16x16x32_bf16 v[114:117], v[184:187], v[192:195], v[114:117]
	v_mfma_f32_16x16x32_bf16 v[102:105], v[172:175], v[196:199], v[102:105]
	v_mfma_f32_16x16x32_bf16 v[102:105], v[176:179], v[200:203], v[102:105]
	v_mfma_f32_16x16x32_bf16 v[98:101], v[180:183], v[196:199], v[98:101]
	v_mfma_f32_16x16x32_bf16 v[98:101], v[184:187], v[200:203], v[98:101]
	v_mfma_f32_16x16x32_bf16 v[86:89], v[172:175], v[204:207], v[86:89]
	v_mfma_f32_16x16x32_bf16 v[86:89], v[176:179], v[208:211], v[86:89]
	v_mfma_f32_16x16x32_bf16 v[82:85], v[180:183], v[204:207], v[82:85]
	v_mfma_f32_16x16x32_bf16 v[82:85], v[184:187], v[208:211], v[82:85]
	v_mfma_f32_16x16x32_bf16 v[70:73], v[172:175], v[214:217], v[70:73]
	v_mfma_f32_16x16x32_bf16 v[70:73], v[176:179], v[218:221], v[70:73]
	v_mfma_f32_16x16x32_bf16 v[66:69], v[180:183], v[214:217], v[66:69]
	v_mfma_f32_16x16x32_bf16 v[66:69], v[184:187], v[218:221], v[66:69]
	s_barrier
	s_mov_b32 m0, s48
	v_lshl_add_u64 v[222:223], s[38:39], 0, v[132:133]
	s_add_u32 s66, s38, 0x108000
	ds_read_b128 v[188:191], v152 offset:16384
	ds_read_b128 v[192:195], v152 offset:17408
	ds_read_b128 v[196:199], v152 offset:18432
	ds_read_b128 v[200:203], v152 offset:19456
	ds_read_b128 v[204:207], v152 offset:20480
	ds_read_b128 v[208:211], v152 offset:21504
	ds_read_b128 v[214:217], v152 offset:22528
	ds_read_b128 v[218:221], v152 offset:23552
	global_load_lds_dwordx4 v[222:223], off
	v_lshl_add_u64 v[224:225], s[38:39], 0, v[136:137]
	s_mov_b32 m0, s49
	s_addc_u32 s67, s39, 0
	global_load_lds_dwordx4 v[224:225], off
	v_lshl_add_u64 v[226:227], s[66:67], 0, v[132:133]
	s_mov_b32 m0, s50
	s_nop 0
	global_load_lds_dwordx4 v[226:227], off
	v_lshl_add_u64 v[226:227], s[66:67], 0, v[136:137]
	s_mov_b32 m0, s51
	s_nop 0
	global_load_lds_dwordx4 v[226:227], off
	v_lshl_add_u64 v[226:227], s[40:41], 0, v[130:131]
	s_mov_b32 m0, s3
	s_nop 0
	global_load_lds_dwordx4 v[226:227], off
	v_lshl_add_u64 v[226:227], s[40:41], 0, v[134:135]
	s_mov_b32 m0, s33
	s_nop 0
	global_load_lds_dwordx4 v[226:227], off
	s_waitcnt vmcnt(8)
	s_waitcnt lgkmcnt(0)
	s_barrier
	s_waitcnt lgkmcnt(0)
	v_mfma_f32_16x16x32_bf16 v[62:65], v[156:159], v[188:191], v[62:65]
	v_mfma_f32_16x16x32_bf16 v[62:65], v[160:163], v[192:195], v[62:65]
	v_mfma_f32_16x16x32_bf16 v[58:61], v[164:167], v[188:191], v[58:61]
	v_mfma_f32_16x16x32_bf16 v[58:61], v[168:171], v[192:195], v[58:61]
	v_mfma_f32_16x16x32_bf16 v[46:49], v[156:159], v[196:199], v[46:49]
	v_mfma_f32_16x16x32_bf16 v[46:49], v[160:163], v[200:203], v[46:49]
	v_mfma_f32_16x16x32_bf16 v[42:45], v[164:167], v[196:199], v[42:45]
	v_mfma_f32_16x16x32_bf16 v[42:45], v[168:171], v[200:203], v[42:45]
	v_mfma_f32_16x16x32_bf16 v[30:33], v[156:159], v[204:207], v[30:33]
	v_mfma_f32_16x16x32_bf16 v[30:33], v[160:163], v[208:211], v[30:33]
	v_mfma_f32_16x16x32_bf16 v[26:29], v[164:167], v[204:207], v[26:29]
	v_mfma_f32_16x16x32_bf16 v[26:29], v[168:171], v[208:211], v[26:29]
	v_mfma_f32_16x16x32_bf16 v[14:17], v[156:159], v[214:217], v[14:17]
	v_mfma_f32_16x16x32_bf16 v[14:17], v[160:163], v[218:221], v[14:17]
	v_mfma_f32_16x16x32_bf16 v[10:13], v[164:167], v[214:217], v[10:13]
	v_mfma_f32_16x16x32_bf16 v[10:13], v[168:171], v[218:221], v[10:13]
	v_mfma_f32_16x16x32_bf16 v[54:57], v[172:175], v[188:191], v[54:57]
	v_mfma_f32_16x16x32_bf16 v[54:57], v[176:179], v[192:195], v[54:57]
	v_mfma_f32_16x16x32_bf16 v[50:53], v[180:183], v[188:191], v[50:53]
	v_mfma_f32_16x16x32_bf16 v[50:53], v[184:187], v[192:195], v[50:53]
	v_mfma_f32_16x16x32_bf16 v[38:41], v[172:175], v[196:199], v[38:41]
	v_mfma_f32_16x16x32_bf16 v[38:41], v[176:179], v[200:203], v[38:41]
	v_mfma_f32_16x16x32_bf16 v[34:37], v[180:183], v[196:199], v[34:37]
	v_mfma_f32_16x16x32_bf16 v[34:37], v[184:187], v[200:203], v[34:37]
	v_mfma_f32_16x16x32_bf16 v[22:25], v[172:175], v[204:207], v[22:25]
	v_mfma_f32_16x16x32_bf16 v[22:25], v[176:179], v[208:211], v[22:25]
	v_mfma_f32_16x16x32_bf16 v[18:21], v[180:183], v[204:207], v[18:21]
	v_mfma_f32_16x16x32_bf16 v[18:21], v[184:187], v[208:211], v[18:21]
	v_mfma_f32_16x16x32_bf16 v[6:9], v[172:175], v[214:217], v[6:9]
	v_mfma_f32_16x16x32_bf16 v[6:9], v[176:179], v[218:221], v[6:9]
	v_mfma_f32_16x16x32_bf16 v[2:5], v[180:183], v[214:217], v[2:5]
	v_mfma_f32_16x16x32_bf16 v[2:5], v[184:187], v[218:221], v[2:5]
	s_barrier
	ds_read_b128 v[156:159], v153
	ds_read_b128 v[160:163], v153 offset:1024
	ds_read_b128 v[164:167], v153 offset:2048
	ds_read_b128 v[168:171], v153 offset:3072
	ds_read_b128 v[172:175], v154
	ds_read_b128 v[176:179], v154 offset:1024
	ds_read_b128 v[180:183], v154 offset:2048
	ds_read_b128 v[184:187], v154 offset:3072
	s_add_u32 s40, s40, 0x108000
	s_addc_u32 s41, s41, 0
	s_mov_b32 m0, s42
	v_lshl_add_u64 v[226:227], s[40:41], 0, v[130:131]
	ds_read_b128 v[188:191], v152 offset:32768
	ds_read_b128 v[192:195], v152 offset:33792
	ds_read_b128 v[196:199], v152 offset:34816
	ds_read_b128 v[200:203], v152 offset:35840
	ds_read_b128 v[204:207], v152 offset:36864
	ds_read_b128 v[208:211], v152 offset:37888
	ds_read_b128 v[214:217], v152 offset:38912
	ds_read_b128 v[218:221], v152 offset:39936
	global_load_lds_dwordx4 v[226:227], off
	v_lshl_add_u64 v[226:227], s[40:41], 0, v[134:135]
	s_mov_b32 m0, s43
	s_nop 0
	global_load_lds_dwordx4 v[226:227], off
	s_waitcnt vmcnt(8)
	s_waitcnt lgkmcnt(0)
	s_barrier
	s_waitcnt lgkmcnt(0)
	v_mfma_f32_16x16x32_bf16 v[126:129], v[156:159], v[188:191], v[126:129]
	v_mfma_f32_16x16x32_bf16 v[126:129], v[160:163], v[192:195], v[126:129]
	v_mfma_f32_16x16x32_bf16 v[122:125], v[164:167], v[188:191], v[122:125]
	v_mfma_f32_16x16x32_bf16 v[122:125], v[168:171], v[192:195], v[122:125]
	v_mfma_f32_16x16x32_bf16 v[110:113], v[156:159], v[196:199], v[110:113]
	v_mfma_f32_16x16x32_bf16 v[110:113], v[160:163], v[200:203], v[110:113]
	v_mfma_f32_16x16x32_bf16 v[106:109], v[164:167], v[196:199], v[106:109]
	v_mfma_f32_16x16x32_bf16 v[106:109], v[168:171], v[200:203], v[106:109]
	v_mfma_f32_16x16x32_bf16 v[94:97], v[156:159], v[204:207], v[94:97]
	v_mfma_f32_16x16x32_bf16 v[94:97], v[160:163], v[208:211], v[94:97]
	v_mfma_f32_16x16x32_bf16 v[90:93], v[164:167], v[204:207], v[90:93]
	v_mfma_f32_16x16x32_bf16 v[90:93], v[168:171], v[208:211], v[90:93]
	v_mfma_f32_16x16x32_bf16 v[78:81], v[156:159], v[214:217], v[78:81]
	v_mfma_f32_16x16x32_bf16 v[78:81], v[160:163], v[218:221], v[78:81]
	v_mfma_f32_16x16x32_bf16 v[74:77], v[164:167], v[214:217], v[74:77]
	v_mfma_f32_16x16x32_bf16 v[74:77], v[168:171], v[218:221], v[74:77]
	v_mfma_f32_16x16x32_bf16 v[118:121], v[172:175], v[188:191], v[118:121]
	v_mfma_f32_16x16x32_bf16 v[118:121], v[176:179], v[192:195], v[118:121]
	v_mfma_f32_16x16x32_bf16 v[114:117], v[180:183], v[188:191], v[114:117]
	v_mfma_f32_16x16x32_bf16 v[114:117], v[184:187], v[192:195], v[114:117]
	v_mfma_f32_16x16x32_bf16 v[102:105], v[172:175], v[196:199], v[102:105]
	v_mfma_f32_16x16x32_bf16 v[102:105], v[176:179], v[200:203], v[102:105]
	v_mfma_f32_16x16x32_bf16 v[98:101], v[180:183], v[196:199], v[98:101]
	v_mfma_f32_16x16x32_bf16 v[98:101], v[184:187], v[200:203], v[98:101]
	v_mfma_f32_16x16x32_bf16 v[86:89], v[172:175], v[204:207], v[86:89]
	v_mfma_f32_16x16x32_bf16 v[86:89], v[176:179], v[208:211], v[86:89]
	v_mfma_f32_16x16x32_bf16 v[82:85], v[180:183], v[204:207], v[82:85]
	v_mfma_f32_16x16x32_bf16 v[82:85], v[184:187], v[208:211], v[82:85]
	v_mfma_f32_16x16x32_bf16 v[70:73], v[172:175], v[214:217], v[70:73]
	v_mfma_f32_16x16x32_bf16 v[70:73], v[176:179], v[218:221], v[70:73]
	v_mfma_f32_16x16x32_bf16 v[66:69], v[180:183], v[214:217], v[66:69]
	v_mfma_f32_16x16x32_bf16 v[66:69], v[184:187], v[218:221], v[66:69]
	s_barrier
	s_mov_b32 m0, s53
	v_lshl_add_u64 v[222:223], v[222:223], 0, s[16:17]
	s_add_u32 s38, s38, 0x108080
	ds_read_b128 v[188:191], v152 offset:49152
	ds_read_b128 v[192:195], v152 offset:50176
	ds_read_b128 v[196:199], v152 offset:51200
	ds_read_b128 v[200:203], v152 offset:52224
	ds_read_b128 v[204:207], v152 offset:53248
	ds_read_b128 v[208:211], v152 offset:54272
	ds_read_b128 v[214:217], v152 offset:55296
	ds_read_b128 v[218:221], v152 offset:56320
	global_load_lds_dwordx4 v[222:223], off
	v_lshl_add_u64 v[222:223], v[224:225], 0, s[16:17]
	s_mov_b32 m0, s54
	s_addc_u32 s39, s39, 0
	s_add_i32 s40, s52, s2
	global_load_lds_dwordx4 v[222:223], off
	v_lshl_add_u64 v[222:223], s[38:39], 0, v[132:133]
	s_mov_b32 m0, s40
	s_nop 0
	global_load_lds_dwordx4 v[222:223], off
	v_lshl_add_u64 v[222:223], s[38:39], 0, v[136:137]
	s_add_i32 m0, s40, 0x2000
	s_nop 0
	global_load_lds_dwordx4 v[222:223], off
	v_lshl_add_u64 v[222:223], s[36:37], 0, v[130:131]
	s_mov_b32 m0, s44
	s_nop 0
	global_load_lds_dwordx4 v[222:223], off
	v_lshl_add_u64 v[222:223], s[36:37], 0, v[134:135]
	s_mov_b32 m0, s45
	s_nop 0
	global_load_lds_dwordx4 v[222:223], off
	s_waitcnt vmcnt(8)
	s_waitcnt lgkmcnt(0)
	s_barrier
	s_waitcnt lgkmcnt(0)
	v_mfma_f32_16x16x32_bf16 v[62:65], v[156:159], v[188:191], v[62:65]
	v_mfma_f32_16x16x32_bf16 v[62:65], v[160:163], v[192:195], v[62:65]
	v_mfma_f32_16x16x32_bf16 v[58:61], v[164:167], v[188:191], v[58:61]
	v_mfma_f32_16x16x32_bf16 v[58:61], v[168:171], v[192:195], v[58:61]
	v_mfma_f32_16x16x32_bf16 v[46:49], v[156:159], v[196:199], v[46:49]
	v_mfma_f32_16x16x32_bf16 v[46:49], v[160:163], v[200:203], v[46:49]
	v_mfma_f32_16x16x32_bf16 v[42:45], v[164:167], v[196:199], v[42:45]
	v_mfma_f32_16x16x32_bf16 v[42:45], v[168:171], v[200:203], v[42:45]
	v_mfma_f32_16x16x32_bf16 v[30:33], v[156:159], v[204:207], v[30:33]
	v_mfma_f32_16x16x32_bf16 v[30:33], v[160:163], v[208:211], v[30:33]
	v_mfma_f32_16x16x32_bf16 v[26:29], v[164:167], v[204:207], v[26:29]
	v_mfma_f32_16x16x32_bf16 v[26:29], v[168:171], v[208:211], v[26:29]
	v_mfma_f32_16x16x32_bf16 v[14:17], v[156:159], v[214:217], v[14:17]
	v_mfma_f32_16x16x32_bf16 v[14:17], v[160:163], v[218:221], v[14:17]
	v_mfma_f32_16x16x32_bf16 v[10:13], v[164:167], v[214:217], v[10:13]
	v_mfma_f32_16x16x32_bf16 v[10:13], v[168:171], v[218:221], v[10:13]
	v_mfma_f32_16x16x32_bf16 v[54:57], v[172:175], v[188:191], v[54:57]
	v_mfma_f32_16x16x32_bf16 v[54:57], v[176:179], v[192:195], v[54:57]
	v_mfma_f32_16x16x32_bf16 v[50:53], v[180:183], v[188:191], v[50:53]
	v_mfma_f32_16x16x32_bf16 v[50:53], v[184:187], v[192:195], v[50:53]
	v_mfma_f32_16x16x32_bf16 v[38:41], v[172:175], v[196:199], v[38:41]
	v_mfma_f32_16x16x32_bf16 v[38:41], v[176:179], v[200:203], v[38:41]
	v_mfma_f32_16x16x32_bf16 v[34:37], v[180:183], v[196:199], v[34:37]
	v_mfma_f32_16x16x32_bf16 v[34:37], v[184:187], v[200:203], v[34:37]
	v_mfma_f32_16x16x32_bf16 v[22:25], v[172:175], v[204:207], v[22:25]
	v_mfma_f32_16x16x32_bf16 v[22:25], v[176:179], v[208:211], v[22:25]
	v_mfma_f32_16x16x32_bf16 v[18:21], v[180:183], v[204:207], v[18:21]
	v_mfma_f32_16x16x32_bf16 v[18:21], v[184:187], v[208:211], v[18:21]
	v_mfma_f32_16x16x32_bf16 v[6:9], v[172:175], v[214:217], v[6:9]
	v_mfma_f32_16x16x32_bf16 v[6:9], v[176:179], v[218:221], v[6:9]
	v_mfma_f32_16x16x32_bf16 v[2:5], v[180:183], v[214:217], v[2:5]
	v_mfma_f32_16x16x32_bf16 v[2:5], v[184:187], v[218:221], v[2:5]
	s_barrier
	s_add_i32 s64, s64, 2
	s_add_u32 s34, s34, 0x100
	s_addc_u32 s35, s35, 0
	s_cmp_gt_u32 s64, 61
	s_cbranch_scc0 .LBB0_235
	s_and_b64 vcc, exec, s[20:21]
	s_cbranch_vccz .LBB0_238
	s_barrier

.LBB0_434:
	ds_read_b128 v[134:137], v204
	ds_read_b128 v[138:141], v204 offset:1024
	ds_read_b128 v[142:145], v204 offset:2048
	ds_read_b128 v[146:149], v204 offset:3072
	ds_read_b128 v[150:153], v205
	ds_read_b128 v[154:157], v205 offset:1024
	ds_read_b128 v[158:161], v205 offset:2048
	ds_read_b128 v[162:165], v205 offset:3072
	s_add_u32 s34, s22, s30
	s_addc_u32 s35, s23, s31
	s_add_u32 s38, s34, 0x100
	s_addc_u32 s39, s35, 0
	s_add_u32 s36, s60, s30
	s_addc_u32 s37, s61, s31
	s_add_u32 s34, s34, 0x180
	s_addc_u32 s35, s35, 0
	s_cmpk_eq_i32 s30, 0xb00
	s_cselect_b32 s35, s59, s35
	s_cselect_b32 s34, s58, s34
	s_cselect_b32 s37, s21, s37
	s_cselect_b32 s36, s20, s36
	s_cselect_b32 s39, s17, s39
	s_cselect_b32 s38, s16, s38
	v_lshl_add_u64 v[200:201], v[130:131], 0, s[30:31]
	s_add_i32 m0, s3, 0xc000
	ds_read_b128 v[166:169], v206
	ds_read_b128 v[170:173], v206 offset:1024
	ds_read_b128 v[174:177], v206 offset:2048
	ds_read_b128 v[178:181], v206 offset:3072
	ds_read_b128 v[182:185], v206 offset:4096
	ds_read_b128 v[208:211], v206 offset:5120
	ds_read_b128 v[214:217], v206 offset:6144
	ds_read_b128 v[218:221], v206 offset:7168
	global_load_lds_dwordx4 v[200:201], off
	v_lshl_add_u64 v[200:201], v[132:133], 0, s[30:31]
	s_add_i32 m0, s3, 0xe000
	s_nop 0
	global_load_lds_dwordx4 v[200:201], off
	s_waitcnt vmcnt(8)
	s_waitcnt lgkmcnt(0)
	s_barrier
	s_waitcnt lgkmcnt(0)
	v_mfma_f32_16x16x32_bf16 v[126:129], v[134:137], v[166:169], v[126:129]
	v_mfma_f32_16x16x32_bf16 v[126:129], v[138:141], v[170:173], v[126:129]
	v_mfma_f32_16x16x32_bf16 v[122:125], v[142:145], v[166:169], v[122:125]
	v_mfma_f32_16x16x32_bf16 v[122:125], v[146:149], v[170:173], v[122:125]
	v_mfma_f32_16x16x32_bf16 v[110:113], v[134:137], v[174:177], v[110:113]
	v_mfma_f32_16x16x32_bf16 v[110:113], v[138:141], v[178:181], v[110:113]
	v_mfma_f32_16x16x32_bf16 v[106:109], v[142:145], v[174:177], v[106:109]
	v_mfma_f32_16x16x32_bf16 v[106:109], v[146:149], v[178:181], v[106:109]
	v_mfma_f32_16x16x32_bf16 v[94:97], v[134:137], v[182:185], v[94:97]
	v_mfma_f32_16x16x32_bf16 v[94:97], v[138:141], v[208:211], v[94:97]
	v_mfma_f32_16x16x32_bf16 v[90:93], v[142:145], v[182:185], v[90:93]
	v_mfma_f32_16x16x32_bf16 v[90:93], v[146:149], v[208:211], v[90:93]
	v_mfma_f32_16x16x32_bf16 v[78:81], v[134:137], v[214:217], v[78:81]
	v_mfma_f32_16x16x32_bf16 v[78:81], v[138:141], v[218:221], v[78:81]
	v_mfma_f32_16x16x32_bf16 v[74:77], v[142:145], v[214:217], v[74:77]
	v_mfma_f32_16x16x32_bf16 v[74:77], v[146:149], v[218:221], v[74:77]
	v_mfma_f32_16x16x32_bf16 v[118:121], v[150:153], v[166:169], v[118:121]
	v_mfma_f32_16x16x32_bf16 v[118:121], v[154:157], v[170:173], v[118:121]
	v_mfma_f32_16x16x32_bf16 v[114:117], v[158:161], v[166:169], v[114:117]
	v_mfma_f32_16x16x32_bf16 v[114:117], v[162:165], v[170:173], v[114:117]
	v_mfma_f32_16x16x32_bf16 v[102:105], v[150:153], v[174:177], v[102:105]
	v_mfma_f32_16x16x32_bf16 v[102:105], v[154:157], v[178:181], v[102:105]
	v_mfma_f32_16x16x32_bf16 v[98:101], v[158:161], v[174:177], v[98:101]
	v_mfma_f32_16x16x32_bf16 v[98:101], v[162:165], v[178:181], v[98:101]
	v_mfma_f32_16x16x32_bf16 v[86:89], v[150:153], v[182:185], v[86:89]
	v_mfma_f32_16x16x32_bf16 v[86:89], v[154:157], v[208:211], v[86:89]
	v_mfma_f32_16x16x32_bf16 v[82:85], v[158:161], v[182:185], v[82:85]
	v_mfma_f32_16x16x32_bf16 v[82:85], v[162:165], v[208:211], v[82:85]
	v_mfma_f32_16x16x32_bf16 v[70:73], v[150:153], v[214:217], v[70:73]
	v_mfma_f32_16x16x32_bf16 v[70:73], v[154:157], v[218:221], v[70:73]
	v_mfma_f32_16x16x32_bf16 v[66:69], v[158:161], v[214:217], v[66:69]
	v_mfma_f32_16x16x32_bf16 v[66:69], v[162:165], v[218:221], v[66:69]
	s_barrier
	s_add_i32 s63, s52, s2
	v_lshl_add_u64 v[200:201], s[36:37], 0, v[188:189]
	s_mov_b32 m0, s63
	ds_read_b128 v[166:169], v206 offset:16384
	ds_read_b128 v[170:173], v206 offset:17408
	ds_read_b128 v[174:177], v206 offset:18432
	ds_read_b128 v[178:181], v206 offset:19456
	ds_read_b128 v[182:185], v206 offset:20480
	ds_read_b128 v[208:211], v206 offset:21504
	ds_read_b128 v[214:217], v206 offset:22528
	ds_read_b128 v[218:221], v206 offset:23552
	global_load_lds_dwordx4 v[200:201], off
	s_add_i32 m0, s63, 0x2000
	s_add_u32 s64, s36, 0x68000
	v_lshl_add_u64 v[222:223], s[36:37], 0, v[192:193]
	s_addc_u32 s65, s37, 0
	s_add_i32 s63, s53, s2
	global_load_lds_dwordx4 v[222:223], off
	v_lshl_add_u64 v[224:225], s[64:65], 0, v[188:189]
	s_mov_b32 m0, s63
	s_nop 0
	global_load_lds_dwordx4 v[224:225], off
	v_lshl_add_u64 v[224:225], s[64:65], 0, v[192:193]
	s_add_i32 m0, s63, 0x2000
	s_nop 0
	global_load_lds_dwordx4 v[224:225], off
	v_lshl_add_u64 v[224:225], s[38:39], 0, v[186:187]
	s_mov_b32 m0, s3
	s_nop 0
	global_load_lds_dwordx4 v[224:225], off
	v_lshl_add_u64 v[224:225], s[38:39], 0, v[190:191]
	s_mov_b32 m0, s33
	s_nop 0
	global_load_lds_dwordx4 v[224:225], off
	s_waitcnt vmcnt(8)
	s_waitcnt lgkmcnt(0)
	s_barrier
	s_waitcnt lgkmcnt(0)
	v_mfma_f32_16x16x32_bf16 v[62:65], v[134:137], v[166:169], v[62:65]
	v_mfma_f32_16x16x32_bf16 v[62:65], v[138:141], v[170:173], v[62:65]
	v_mfma_f32_16x16x32_bf16 v[58:61], v[142:145], v[166:169], v[58:61]
	v_mfma_f32_16x16x32_bf16 v[58:61], v[146:149], v[170:173], v[58:61]
	v_mfma_f32_16x16x32_bf16 v[46:49], v[134:137], v[174:177], v[46:49]
	v_mfma_f32_16x16x32_bf16 v[46:49], v[138:141], v[178:181], v[46:49]
	v_mfma_f32_16x16x32_bf16 v[42:45], v[142:145], v[174:177], v[42:45]
	v_mfma_f32_16x16x32_bf16 v[42:45], v[146:149], v[178:181], v[42:45]
	v_mfma_f32_16x16x32_bf16 v[30:33], v[134:137], v[182:185], v[30:33]
	v_mfma_f32_16x16x32_bf16 v[30:33], v[138:141], v[208:211], v[30:33]
	v_mfma_f32_16x16x32_bf16 v[26:29], v[142:145], v[182:185], v[26:29]
	v_mfma_f32_16x16x32_bf16 v[26:29], v[146:149], v[208:211], v[26:29]
	v_mfma_f32_16x16x32_bf16 v[14:17], v[134:137], v[214:217], v[14:17]
	v_mfma_f32_16x16x32_bf16 v[14:17], v[138:141], v[218:221], v[14:17]
	v_mfma_f32_16x16x32_bf16 v[10:13], v[142:145], v[214:217], v[10:13]
	v_mfma_f32_16x16x32_bf16 v[10:13], v[146:149], v[218:221], v[10:13]
	v_mfma_f32_16x16x32_bf16 v[54:57], v[150:153], v[166:169], v[54:57]
	v_mfma_f32_16x16x32_bf16 v[54:57], v[154:157], v[170:173], v[54:57]
	v_mfma_f32_16x16x32_bf16 v[50:53], v[158:161], v[166:169], v[50:53]
	v_mfma_f32_16x16x32_bf16 v[50:53], v[162:165], v[170:173], v[50:53]
	v_mfma_f32_16x16x32_bf16 v[38:41], v[150:153], v[174:177], v[38:41]
	v_mfma_f32_16x16x32_bf16 v[38:41], v[154:157], v[178:181], v[38:41]
	v_mfma_f32_16x16x32_bf16 v[34:37], v[158:161], v[174:177], v[34:37]
	v_mfma_f32_16x16x32_bf16 v[34:37], v[162:165], v[178:181], v[34:37]
	v_mfma_f32_16x16x32_bf16 v[22:25], v[150:153], v[182:185], v[22:25]
	v_mfma_f32_16x16x32_bf16 v[22:25], v[154:157], v[208:211], v[22:25]
	v_mfma_f32_16x16x32_bf16 v[18:21], v[158:161], v[182:185], v[18:21]
	v_mfma_f32_16x16x32_bf16 v[18:21], v[162:165], v[208:211], v[18:21]
	v_mfma_f32_16x16x32_bf16 v[6:9], v[150:153], v[214:217], v[6:9]
	v_mfma_f32_16x16x32_bf16 v[6:9], v[154:157], v[218:221], v[6:9]
	v_mfma_f32_16x16x32_bf16 v[2:5], v[158:161], v[214:217], v[2:5]
	v_mfma_f32_16x16x32_bf16 v[2:5], v[162:165], v[218:221], v[2:5]
	s_barrier
	s_add_i32 s63, 0, 0x18000
	s_add_i32 s64, 0, 0x1c000
	v_add_u32_e32 v146, s63, v202
	v_add_u32_e32 v162, s64, v202
	ds_read_b128 v[134:137], v146
	ds_read_b128 v[138:141], v146 offset:1024
	ds_read_b128 v[142:145], v146 offset:2048
	ds_read_b128 v[146:149], v146 offset:3072
	ds_read_b128 v[150:153], v162
	ds_read_b128 v[154:157], v162 offset:1024
	ds_read_b128 v[158:161], v162 offset:2048
	ds_read_b128 v[162:165], v162 offset:3072
	s_add_u32 s38, s38, 0x188000
	s_addc_u32 s39, s39, 0
	s_mov_b32 m0, s40
	v_lshl_add_u64 v[224:225], s[38:39], 0, v[186:187]
	ds_read_b128 v[166:169], v206 offset:32768
	ds_read_b128 v[170:173], v206 offset:33792
	ds_read_b128 v[174:177], v206 offset:34816
	ds_read_b128 v[178:181], v206 offset:35840
	ds_read_b128 v[182:185], v206 offset:36864
	ds_read_b128 v[208:211], v206 offset:37888
	ds_read_b128 v[214:217], v206 offset:38912
	ds_read_b128 v[218:221], v206 offset:39936
	global_load_lds_dwordx4 v[224:225], off
	v_lshl_add_u64 v[224:225], s[38:39], 0, v[190:191]
	s_mov_b32 m0, s41
	s_nop 0
	global_load_lds_dwordx4 v[224:225], off
	s_waitcnt vmcnt(8)
	s_waitcnt lgkmcnt(0)
	s_barrier
	s_waitcnt lgkmcnt(0)
	v_mfma_f32_16x16x32_bf16 v[126:129], v[134:137], v[166:169], v[126:129]
	v_mfma_f32_16x16x32_bf16 v[126:129], v[138:141], v[170:173], v[126:129]
	v_mfma_f32_16x16x32_bf16 v[122:125], v[142:145], v[166:169], v[122:125]
	v_mfma_f32_16x16x32_bf16 v[122:125], v[146:149], v[170:173], v[122:125]
	v_mfma_f32_16x16x32_bf16 v[110:113], v[134:137], v[174:177], v[110:113]
	v_mfma_f32_16x16x32_bf16 v[110:113], v[138:141], v[178:181], v[110:113]
	v_mfma_f32_16x16x32_bf16 v[106:109], v[142:145], v[174:177], v[106:109]
	v_mfma_f32_16x16x32_bf16 v[106:109], v[146:149], v[178:181], v[106:109]
	v_mfma_f32_16x16x32_bf16 v[94:97], v[134:137], v[182:185], v[94:97]
	v_mfma_f32_16x16x32_bf16 v[94:97], v[138:141], v[208:211], v[94:97]
	v_mfma_f32_16x16x32_bf16 v[90:93], v[142:145], v[182:185], v[90:93]
	v_mfma_f32_16x16x32_bf16 v[90:93], v[146:149], v[208:211], v[90:93]
	v_mfma_f32_16x16x32_bf16 v[78:81], v[134:137], v[214:217], v[78:81]
	v_mfma_f32_16x16x32_bf16 v[78:81], v[138:141], v[218:221], v[78:81]
	v_mfma_f32_16x16x32_bf16 v[74:77], v[142:145], v[214:217], v[74:77]
	v_mfma_f32_16x16x32_bf16 v[74:77], v[146:149], v[218:221], v[74:77]
	v_mfma_f32_16x16x32_bf16 v[118:121], v[150:153], v[166:169], v[118:121]
	v_mfma_f32_16x16x32_bf16 v[118:121], v[154:157], v[170:173], v[118:121]
	v_mfma_f32_16x16x32_bf16 v[114:117], v[158:161], v[166:169], v[114:117]
	v_mfma_f32_16x16x32_bf16 v[114:117], v[162:165], v[170:173], v[114:117]
	v_mfma_f32_16x16x32_bf16 v[102:105], v[150:153], v[174:177], v[102:105]
	v_mfma_f32_16x16x32_bf16 v[102:105], v[154:157], v[178:181], v[102:105]
	v_mfma_f32_16x16x32_bf16 v[98:101], v[158:161], v[174:177], v[98:101]
	v_mfma_f32_16x16x32_bf16 v[98:101], v[162:165], v[178:181], v[98:101]
	v_mfma_f32_16x16x32_bf16 v[86:89], v[150:153], v[182:185], v[86:89]
	v_mfma_f32_16x16x32_bf16 v[86:89], v[154:157], v[208:211], v[86:89]
	v_mfma_f32_16x16x32_bf16 v[82:85], v[158:161], v[182:185], v[82:85]
	v_mfma_f32_16x16x32_bf16 v[82:85], v[162:165], v[208:211], v[82:85]
	v_mfma_f32_16x16x32_bf16 v[70:73], v[150:153], v[214:217], v[70:73]
	v_mfma_f32_16x16x32_bf16 v[70:73], v[154:157], v[218:221], v[70:73]
	v_mfma_f32_16x16x32_bf16 v[66:69], v[158:161], v[214:217], v[66:69]
	v_mfma_f32_16x16x32_bf16 v[66:69], v[162:165], v[218:221], v[66:69]
	s_barrier
	s_add_i32 s38, s63, s2
	v_lshl_add_u64 v[200:201], v[200:201], 0, s[12:13]
	s_mov_b32 m0, s38
	ds_read_b128 v[166:169], v206 offset:49152
	ds_read_b128 v[170:173], v206 offset:50176
	ds_read_b128 v[174:177], v206 offset:51200
	ds_read_b128 v[178:181], v206 offset:52224
	ds_read_b128 v[182:185], v206 offset:53248
	ds_read_b128 v[208:211], v206 offset:54272
	ds_read_b128 v[214:217], v206 offset:55296
	ds_read_b128 v[218:221], v206 offset:56320
	global_load_lds_dwordx4 v[200:201], off
	s_add_i32 m0, s38, 0x2000
	s_add_u32 s36, s36, 0x68080
	v_lshl_add_u64 v[200:201], v[222:223], 0, s[12:13]
	s_addc_u32 s37, s37, 0
	s_add_i32 s38, s64, s2
	global_load_lds_dwordx4 v[200:201], off
	v_lshl_add_u64 v[200:201], s[36:37], 0, v[188:189]
	s_mov_b32 m0, s38
	s_nop 0
	global_load_lds_dwordx4 v[200:201], off
	v_lshl_add_u64 v[200:201], s[36:37], 0, v[192:193]
	s_add_i32 m0, s38, 0x2000
	s_nop 0
	global_load_lds_dwordx4 v[200:201], off
	v_lshl_add_u64 v[200:201], s[34:35], 0, v[186:187]
	s_mov_b32 m0, s50
	s_nop 0
	global_load_lds_dwordx4 v[200:201], off
	v_lshl_add_u64 v[200:201], s[34:35], 0, v[190:191]
	s_mov_b32 m0, s51
	s_nop 0
	global_load_lds_dwordx4 v[200:201], off
	s_waitcnt vmcnt(8)
	s_waitcnt lgkmcnt(0)
	s_barrier
	s_waitcnt lgkmcnt(0)
	v_mfma_f32_16x16x32_bf16 v[62:65], v[134:137], v[166:169], v[62:65]
	v_mfma_f32_16x16x32_bf16 v[62:65], v[138:141], v[170:173], v[62:65]
	v_mfma_f32_16x16x32_bf16 v[58:61], v[142:145], v[166:169], v[58:61]
	v_mfma_f32_16x16x32_bf16 v[58:61], v[146:149], v[170:173], v[58:61]
	v_mfma_f32_16x16x32_bf16 v[46:49], v[134:137], v[174:177], v[46:49]
	v_mfma_f32_16x16x32_bf16 v[46:49], v[138:141], v[178:181], v[46:49]
	v_mfma_f32_16x16x32_bf16 v[42:45], v[142:145], v[174:177], v[42:45]
	v_mfma_f32_16x16x32_bf16 v[42:45], v[146:149], v[178:181], v[42:45]
	v_mfma_f32_16x16x32_bf16 v[30:33], v[134:137], v[182:185], v[30:33]
	v_mfma_f32_16x16x32_bf16 v[30:33], v[138:141], v[208:211], v[30:33]
	v_mfma_f32_16x16x32_bf16 v[26:29], v[142:145], v[182:185], v[26:29]
	v_mfma_f32_16x16x32_bf16 v[26:29], v[146:149], v[208:211], v[26:29]
	v_mfma_f32_16x16x32_bf16 v[14:17], v[134:137], v[214:217], v[14:17]
	v_mfma_f32_16x16x32_bf16 v[14:17], v[138:141], v[218:221], v[14:17]
	v_mfma_f32_16x16x32_bf16 v[10:13], v[142:145], v[214:217], v[10:13]
	v_mfma_f32_16x16x32_bf16 v[10:13], v[146:149], v[218:221], v[10:13]
	v_mfma_f32_16x16x32_bf16 v[54:57], v[150:153], v[166:169], v[54:57]
	v_mfma_f32_16x16x32_bf16 v[54:57], v[154:157], v[170:173], v[54:57]
	v_mfma_f32_16x16x32_bf16 v[50:53], v[158:161], v[166:169], v[50:53]
	v_mfma_f32_16x16x32_bf16 v[50:53], v[162:165], v[170:173], v[50:53]
	v_mfma_f32_16x16x32_bf16 v[38:41], v[150:153], v[174:177], v[38:41]
	v_mfma_f32_16x16x32_bf16 v[38:41], v[154:157], v[178:181], v[38:41]
	v_mfma_f32_16x16x32_bf16 v[34:37], v[158:161], v[174:177], v[34:37]
	v_mfma_f32_16x16x32_bf16 v[34:37], v[162:165], v[178:181], v[34:37]
	v_mfma_f32_16x16x32_bf16 v[22:25], v[150:153], v[182:185], v[22:25]
	v_mfma_f32_16x16x32_bf16 v[22:25], v[154:157], v[208:211], v[22:25]
	v_mfma_f32_16x16x32_bf16 v[18:21], v[158:161], v[182:185], v[18:21]
	v_mfma_f32_16x16x32_bf16 v[18:21], v[162:165], v[208:211], v[18:21]
	v_mfma_f32_16x16x32_bf16 v[6:9], v[150:153], v[214:217], v[6:9]
	v_mfma_f32_16x16x32_bf16 v[6:9], v[154:157], v[218:221], v[6:9]
	v_mfma_f32_16x16x32_bf16 v[2:5], v[158:161], v[214:217], v[2:5]
	v_mfma_f32_16x16x32_bf16 v[2:5], v[162:165], v[218:221], v[2:5]
	s_barrier
	s_add_i32 s62, s62, 2
	s_add_u32 s30, s30, 0x100
	s_addc_u32 s31, s31, 0
	s_cmp_gt_u32 s62, 21
	s_cbranch_scc0 .LBB0_434
	s_and_b64 vcc, exec, s[14:15]
	s_cbranch_vccz .LBB0_437
	s_barrier

.LBB0_519:
	s_add_i32 s39, s56, 0xfffe8000
	s_and_b32 s38, s36, 0x100
	s_and_b32 s39, s39, 0x3e0000
	s_or_b32 s38, s38, s39
	s_add_u32 s57, s34, s38
	s_addc_u32 s59, s35, 0
	s_add_u32 s38, s36, 0x100
	s_addc_u32 s39, s37, 0
	s_add_i32 s41, s56, 0xffff8000
	s_and_b32 s40, s38, 0x100
	s_and_b32 s41, s41, 0x7e0000
	s_or_b32 s40, s41, s40
	s_add_u32 s40, s34, s40
	s_addc_u32 s41, s35, 0
	s_add_u32 s58, s53, s36
	s_addc_u32 s37, s54, s37
	s_add_i32 s42, s36, 0x180
	s_and_b32 s42, s42, 0x180
	s_and_b32 s43, s56, 0x7e0000
	s_or_b32 s42, s43, s42
	s_add_u32 s60, s34, s42
	s_addc_u32 s61, s35, 0
	s_cmpk_eq_i32 s36, 0x3f00
	s_cselect_b32 s43, s1, s41
	s_cselect_b32 s42, s21, s40
	s_cselect_b32 s41, s23, s37
	s_cselect_b32 s40, s22, s58
	s_cselect_b32 s37, s52, s61
	s_cselect_b32 s36, s31, s60
	s_add_i32 s60, 0, 0x10000
	v_add_u32_e32 v1, s60, v199
	ds_read_b128 v[130:133], v1
	ds_read_b128 v[134:137], v1 offset:1024
	ds_read_b128 v[138:141], v1 offset:2048
	ds_read_b128 v[142:145], v1 offset:3072
	ds_read_b128 v[146:149], v201
	ds_read_b128 v[150:153], v201 offset:1024
	ds_read_b128 v[154:157], v201 offset:2048
	ds_read_b128 v[158:161], v201 offset:3072
	s_add_u32 s58, s57, 0x10080
	s_addc_u32 s59, s59, 0
	v_lshl_add_u64 v[208:209], s[58:59], 0, v[178:179]
	s_add_i32 m0, s3, 0xc000
	ds_read_b128 v[162:165], v202
	ds_read_b128 v[166:169], v202 offset:1024
	ds_read_b128 v[170:173], v202 offset:2048
	ds_read_b128 v[174:177], v202 offset:3072
	ds_read_b128 v[186:189], v202 offset:4096
	ds_read_b128 v[190:193], v202 offset:5120
	ds_read_b128 v[194:197], v202 offset:6144
	ds_read_b128 v[204:207], v202 offset:7168
	global_load_lds_dwordx4 v[208:209], off
	v_lshl_add_u64 v[208:209], s[58:59], 0, v[182:183]
	s_add_i32 m0, s3, 0xe000
	s_nop 0
	global_load_lds_dwordx4 v[208:209], off
	s_waitcnt vmcnt(8)
	s_waitcnt lgkmcnt(0)
	s_barrier
	s_waitcnt lgkmcnt(0)
	v_mfma_f32_16x16x32_bf16 v[126:129], v[130:133], v[162:165], v[126:129]
	v_mfma_f32_16x16x32_bf16 v[126:129], v[134:137], v[166:169], v[126:129]
	v_mfma_f32_16x16x32_bf16 v[122:125], v[138:141], v[162:165], v[122:125]
	v_mfma_f32_16x16x32_bf16 v[122:125], v[142:145], v[166:169], v[122:125]
	v_mfma_f32_16x16x32_bf16 v[110:113], v[130:133], v[170:173], v[110:113]
	v_mfma_f32_16x16x32_bf16 v[110:113], v[134:137], v[174:177], v[110:113]
	v_mfma_f32_16x16x32_bf16 v[106:109], v[138:141], v[170:173], v[106:109]
	v_mfma_f32_16x16x32_bf16 v[106:109], v[142:145], v[174:177], v[106:109]
	v_mfma_f32_16x16x32_bf16 v[94:97], v[130:133], v[186:189], v[94:97]
	v_mfma_f32_16x16x32_bf16 v[94:97], v[134:137], v[190:193], v[94:97]
	v_mfma_f32_16x16x32_bf16 v[90:93], v[138:141], v[186:189], v[90:93]
	v_mfma_f32_16x16x32_bf16 v[90:93], v[142:145], v[190:193], v[90:93]
	v_mfma_f32_16x16x32_bf16 v[78:81], v[130:133], v[194:197], v[78:81]
	v_mfma_f32_16x16x32_bf16 v[78:81], v[134:137], v[204:207], v[78:81]
	v_mfma_f32_16x16x32_bf16 v[74:77], v[138:141], v[194:197], v[74:77]
	v_mfma_f32_16x16x32_bf16 v[74:77], v[142:145], v[204:207], v[74:77]
	v_mfma_f32_16x16x32_bf16 v[118:121], v[146:149], v[162:165], v[118:121]
	v_mfma_f32_16x16x32_bf16 v[118:121], v[150:153], v[166:169], v[118:121]
	v_mfma_f32_16x16x32_bf16 v[114:117], v[154:157], v[162:165], v[114:117]
	v_mfma_f32_16x16x32_bf16 v[114:117], v[158:161], v[166:169], v[114:117]
	v_mfma_f32_16x16x32_bf16 v[102:105], v[146:149], v[170:173], v[102:105]
	v_mfma_f32_16x16x32_bf16 v[102:105], v[150:153], v[174:177], v[102:105]
	v_mfma_f32_16x16x32_bf16 v[98:101], v[154:157], v[170:173], v[98:101]
	v_mfma_f32_16x16x32_bf16 v[98:101], v[158:161], v[174:177], v[98:101]
	v_mfma_f32_16x16x32_bf16 v[86:89], v[146:149], v[186:189], v[86:89]
	v_mfma_f32_16x16x32_bf16 v[86:89], v[150:153], v[190:193], v[86:89]
	v_mfma_f32_16x16x32_bf16 v[82:85], v[154:157], v[186:189], v[82:85]
	v_mfma_f32_16x16x32_bf16 v[82:85], v[158:161], v[190:193], v[82:85]
	v_mfma_f32_16x16x32_bf16 v[70:73], v[146:149], v[194:197], v[70:73]
	v_mfma_f32_16x16x32_bf16 v[70:73], v[150:153], v[204:207], v[70:73]
	v_mfma_f32_16x16x32_bf16 v[66:69], v[154:157], v[194:197], v[66:69]
	v_mfma_f32_16x16x32_bf16 v[66:69], v[158:161], v[204:207], v[66:69]
	s_barrier
	s_add_i32 s57, s60, s2
	v_lshl_add_u64 v[208:209], s[40:41], 0, v[180:181]
	s_mov_b32 m0, s57
	ds_read_b128 v[162:165], v202 offset:16384
	ds_read_b128 v[166:169], v202 offset:17408
	ds_read_b128 v[170:173], v202 offset:18432
	ds_read_b128 v[174:177], v202 offset:19456
	ds_read_b128 v[186:189], v202 offset:20480
	ds_read_b128 v[190:193], v202 offset:21504
	ds_read_b128 v[194:197], v202 offset:22528
	ds_read_b128 v[204:207], v202 offset:23552
	global_load_lds_dwordx4 v[208:209], off
	s_add_i32 m0, s57, 0x2000
	s_add_u32 s58, s40, 0x208000
	v_lshl_add_u64 v[210:211], s[40:41], 0, v[184:185]
	s_addc_u32 s59, s41, 0
	s_add_i32 s57, s49, s2
	global_load_lds_dwordx4 v[210:211], off
	v_lshl_add_u64 v[214:215], s[58:59], 0, v[180:181]
	s_mov_b32 m0, s57
	s_nop 0
	global_load_lds_dwordx4 v[214:215], off
	v_lshl_add_u64 v[214:215], s[58:59], 0, v[184:185]
	s_add_i32 m0, s57, 0x2000
	s_nop 0
	global_load_lds_dwordx4 v[214:215], off
	v_lshl_add_u64 v[214:215], s[42:43], 0, v[178:179]
	s_mov_b32 m0, s3
	s_nop 0
	global_load_lds_dwordx4 v[214:215], off
	v_lshl_add_u64 v[214:215], s[42:43], 0, v[182:183]
	s_mov_b32 m0, s33
	s_nop 0
	global_load_lds_dwordx4 v[214:215], off
	s_waitcnt vmcnt(8)
	s_waitcnt lgkmcnt(0)
	s_barrier
	s_waitcnt lgkmcnt(0)
	v_mfma_f32_16x16x32_bf16 v[62:65], v[130:133], v[162:165], v[62:65]
	v_mfma_f32_16x16x32_bf16 v[62:65], v[134:137], v[166:169], v[62:65]
	v_mfma_f32_16x16x32_bf16 v[58:61], v[138:141], v[162:165], v[58:61]
	v_mfma_f32_16x16x32_bf16 v[58:61], v[142:145], v[166:169], v[58:61]
	v_mfma_f32_16x16x32_bf16 v[46:49], v[130:133], v[170:173], v[46:49]
	v_mfma_f32_16x16x32_bf16 v[46:49], v[134:137], v[174:177], v[46:49]
	v_mfma_f32_16x16x32_bf16 v[42:45], v[138:141], v[170:173], v[42:45]
	v_mfma_f32_16x16x32_bf16 v[42:45], v[142:145], v[174:177], v[42:45]
	v_mfma_f32_16x16x32_bf16 v[30:33], v[130:133], v[186:189], v[30:33]
	v_mfma_f32_16x16x32_bf16 v[30:33], v[134:137], v[190:193], v[30:33]
	v_mfma_f32_16x16x32_bf16 v[26:29], v[138:141], v[186:189], v[26:29]
	v_mfma_f32_16x16x32_bf16 v[26:29], v[142:145], v[190:193], v[26:29]
	v_mfma_f32_16x16x32_bf16 v[14:17], v[130:133], v[194:197], v[14:17]
	v_mfma_f32_16x16x32_bf16 v[14:17], v[134:137], v[204:207], v[14:17]
	v_mfma_f32_16x16x32_bf16 v[10:13], v[138:141], v[194:197], v[10:13]
	v_mfma_f32_16x16x32_bf16 v[10:13], v[142:145], v[204:207], v[10:13]
	v_mfma_f32_16x16x32_bf16 v[54:57], v[146:149], v[162:165], v[54:57]
	v_mfma_f32_16x16x32_bf16 v[54:57], v[150:153], v[166:169], v[54:57]
	v_mfma_f32_16x16x32_bf16 v[50:53], v[154:157], v[162:165], v[50:53]
	v_mfma_f32_16x16x32_bf16 v[50:53], v[158:161], v[166:169], v[50:53]
	v_mfma_f32_16x16x32_bf16 v[38:41], v[146:149], v[170:173], v[38:41]
	v_mfma_f32_16x16x32_bf16 v[38:41], v[150:153], v[174:177], v[38:41]
	v_mfma_f32_16x16x32_bf16 v[34:37], v[154:157], v[170:173], v[34:37]
	v_mfma_f32_16x16x32_bf16 v[34:37], v[158:161], v[174:177], v[34:37]
	v_mfma_f32_16x16x32_bf16 v[22:25], v[146:149], v[186:189], v[22:25]
	v_mfma_f32_16x16x32_bf16 v[22:25], v[150:153], v[190:193], v[22:25]
	v_mfma_f32_16x16x32_bf16 v[18:21], v[154:157], v[186:189], v[18:21]
	v_mfma_f32_16x16x32_bf16 v[18:21], v[158:161], v[190:193], v[18:21]
	v_mfma_f32_16x16x32_bf16 v[6:9], v[146:149], v[194:197], v[6:9]
	v_mfma_f32_16x16x32_bf16 v[6:9], v[150:153], v[204:207], v[6:9]
	v_mfma_f32_16x16x32_bf16 v[2:5], v[154:157], v[194:197], v[2:5]
	v_mfma_f32_16x16x32_bf16 v[2:5], v[158:161], v[204:207], v[2:5]
	s_barrier
	s_add_i32 s57, 0, 0x18000
	v_add_u32_e32 v1, s57, v199
	s_add_i32 s58, 0, 0x1c000
	ds_read_b128 v[130:133], v1
	ds_read_b128 v[134:137], v1 offset:1024
	ds_read_b128 v[138:141], v1 offset:2048
	ds_read_b128 v[142:145], v1 offset:3072
	v_add_u32_e32 v1, s58, v199
	ds_read_b128 v[146:149], v1
	ds_read_b128 v[150:153], v1 offset:1024
	ds_read_b128 v[154:157], v1 offset:2048
	ds_read_b128 v[158:161], v1 offset:3072
	s_add_u32 s42, s42, 0x10000
	s_addc_u32 s43, s43, 0
	s_mov_b32 m0, s44
	v_lshl_add_u64 v[214:215], s[42:43], 0, v[178:179]
	ds_read_b128 v[162:165], v202 offset:32768
	ds_read_b128 v[166:169], v202 offset:33792
	ds_read_b128 v[170:173], v202 offset:34816
	ds_read_b128 v[174:177], v202 offset:35840
	ds_read_b128 v[186:189], v202 offset:36864
	ds_read_b128 v[190:193], v202 offset:37888
	ds_read_b128 v[194:197], v202 offset:38912
	ds_read_b128 v[204:207], v202 offset:39936
	global_load_lds_dwordx4 v[214:215], off
	v_lshl_add_u64 v[214:215], s[42:43], 0, v[182:183]
	s_mov_b32 m0, s45
	s_nop 0
	global_load_lds_dwordx4 v[214:215], off
	s_waitcnt vmcnt(8)
	s_waitcnt lgkmcnt(0)
	s_barrier
	s_waitcnt lgkmcnt(0)
	v_mfma_f32_16x16x32_bf16 v[126:129], v[130:133], v[162:165], v[126:129]
	v_mfma_f32_16x16x32_bf16 v[126:129], v[134:137], v[166:169], v[126:129]
	v_mfma_f32_16x16x32_bf16 v[122:125], v[138:141], v[162:165], v[122:125]
	v_mfma_f32_16x16x32_bf16 v[122:125], v[142:145], v[166:169], v[122:125]
	v_mfma_f32_16x16x32_bf16 v[110:113], v[130:133], v[170:173], v[110:113]
	v_mfma_f32_16x16x32_bf16 v[110:113], v[134:137], v[174:177], v[110:113]
	v_mfma_f32_16x16x32_bf16 v[106:109], v[138:141], v[170:173], v[106:109]
	v_mfma_f32_16x16x32_bf16 v[106:109], v[142:145], v[174:177], v[106:109]
	v_mfma_f32_16x16x32_bf16 v[94:97], v[130:133], v[186:189], v[94:97]
	v_mfma_f32_16x16x32_bf16 v[94:97], v[134:137], v[190:193], v[94:97]
	v_mfma_f32_16x16x32_bf16 v[90:93], v[138:141], v[186:189], v[90:93]
	v_mfma_f32_16x16x32_bf16 v[90:93], v[142:145], v[190:193], v[90:93]
	v_mfma_f32_16x16x32_bf16 v[78:81], v[130:133], v[194:197], v[78:81]
	v_mfma_f32_16x16x32_bf16 v[78:81], v[134:137], v[204:207], v[78:81]
	v_mfma_f32_16x16x32_bf16 v[74:77], v[138:141], v[194:197], v[74:77]
	v_mfma_f32_16x16x32_bf16 v[74:77], v[142:145], v[204:207], v[74:77]
	v_mfma_f32_16x16x32_bf16 v[118:121], v[146:149], v[162:165], v[118:121]
	v_mfma_f32_16x16x32_bf16 v[118:121], v[150:153], v[166:169], v[118:121]
	v_mfma_f32_16x16x32_bf16 v[114:117], v[154:157], v[162:165], v[114:117]
	v_mfma_f32_16x16x32_bf16 v[114:117], v[158:161], v[166:169], v[114:117]
	v_mfma_f32_16x16x32_bf16 v[102:105], v[146:149], v[170:173], v[102:105]
	v_mfma_f32_16x16x32_bf16 v[102:105], v[150:153], v[174:177], v[102:105]
	v_mfma_f32_16x16x32_bf16 v[98:101], v[154:157], v[170:173], v[98:101]
	v_mfma_f32_16x16x32_bf16 v[98:101], v[158:161], v[174:177], v[98:101]
	v_mfma_f32_16x16x32_bf16 v[86:89], v[146:149], v[186:189], v[86:89]
	v_mfma_f32_16x16x32_bf16 v[86:89], v[150:153], v[190:193], v[86:89]
	v_mfma_f32_16x16x32_bf16 v[82:85], v[154:157], v[186:189], v[82:85]
	v_mfma_f32_16x16x32_bf16 v[82:85], v[158:161], v[190:193], v[82:85]
	v_mfma_f32_16x16x32_bf16 v[70:73], v[146:149], v[194:197], v[70:73]
	v_mfma_f32_16x16x32_bf16 v[70:73], v[150:153], v[204:207], v[70:73]
	v_mfma_f32_16x16x32_bf16 v[66:69], v[154:157], v[194:197], v[66:69]
	v_mfma_f32_16x16x32_bf16 v[66:69], v[158:161], v[204:207], v[66:69]
	s_barrier
	s_add_i32 s42, s57, s2
	v_lshl_add_u64 v[208:209], v[208:209], 0, s[16:17]
	s_mov_b32 m0, s42
	ds_read_b128 v[162:165], v202 offset:49152
	ds_read_b128 v[166:169], v202 offset:50176
	ds_read_b128 v[170:173], v202 offset:51200
	ds_read_b128 v[174:177], v202 offset:52224
	ds_read_b128 v[186:189], v202 offset:53248
	ds_read_b128 v[190:193], v202 offset:54272
	ds_read_b128 v[194:197], v202 offset:55296
	ds_read_b128 v[204:207], v202 offset:56320
	global_load_lds_dwordx4 v[208:209], off
	s_add_i32 m0, s42, 0x2000
	s_add_u32 s40, s40, 0x208080
	v_lshl_add_u64 v[208:209], v[210:211], 0, s[16:17]
	s_addc_u32 s41, s41, 0
	s_add_i32 s42, s58, s2
	global_load_lds_dwordx4 v[208:209], off
	v_lshl_add_u64 v[208:209], s[40:41], 0, v[180:181]
	s_mov_b32 m0, s42
	s_nop 0
	global_load_lds_dwordx4 v[208:209], off
	v_lshl_add_u64 v[208:209], s[40:41], 0, v[184:185]
	s_add_i32 m0, s42, 0x2000
	s_nop 0
	global_load_lds_dwordx4 v[208:209], off
	v_lshl_add_u64 v[208:209], s[36:37], 0, v[178:179]
	s_mov_b32 m0, s47
	s_nop 0
	global_load_lds_dwordx4 v[208:209], off
	v_lshl_add_u64 v[208:209], s[36:37], 0, v[182:183]
	s_mov_b32 m0, s48
	s_nop 0
	global_load_lds_dwordx4 v[208:209], off
	s_waitcnt vmcnt(8)
	s_waitcnt lgkmcnt(0)
	s_barrier
	s_waitcnt lgkmcnt(0)
	v_mfma_f32_16x16x32_bf16 v[62:65], v[130:133], v[162:165], v[62:65]
	v_mfma_f32_16x16x32_bf16 v[62:65], v[134:137], v[166:169], v[62:65]
	v_mfma_f32_16x16x32_bf16 v[58:61], v[138:141], v[162:165], v[58:61]
	v_mfma_f32_16x16x32_bf16 v[58:61], v[142:145], v[166:169], v[58:61]
	v_mfma_f32_16x16x32_bf16 v[46:49], v[130:133], v[170:173], v[46:49]
	v_mfma_f32_16x16x32_bf16 v[46:49], v[134:137], v[174:177], v[46:49]
	v_mfma_f32_16x16x32_bf16 v[42:45], v[138:141], v[170:173], v[42:45]
	v_mfma_f32_16x16x32_bf16 v[42:45], v[142:145], v[174:177], v[42:45]
	v_mfma_f32_16x16x32_bf16 v[30:33], v[130:133], v[186:189], v[30:33]
	v_mfma_f32_16x16x32_bf16 v[30:33], v[134:137], v[190:193], v[30:33]
	v_mfma_f32_16x16x32_bf16 v[26:29], v[138:141], v[186:189], v[26:29]
	v_mfma_f32_16x16x32_bf16 v[26:29], v[142:145], v[190:193], v[26:29]
	v_mfma_f32_16x16x32_bf16 v[14:17], v[130:133], v[194:197], v[14:17]
	v_mfma_f32_16x16x32_bf16 v[14:17], v[134:137], v[204:207], v[14:17]
	v_mfma_f32_16x16x32_bf16 v[10:13], v[138:141], v[194:197], v[10:13]
	v_mfma_f32_16x16x32_bf16 v[10:13], v[142:145], v[204:207], v[10:13]
	v_mfma_f32_16x16x32_bf16 v[54:57], v[146:149], v[162:165], v[54:57]
	v_mfma_f32_16x16x32_bf16 v[54:57], v[150:153], v[166:169], v[54:57]
	v_mfma_f32_16x16x32_bf16 v[50:53], v[154:157], v[162:165], v[50:53]
	v_mfma_f32_16x16x32_bf16 v[50:53], v[158:161], v[166:169], v[50:53]
	v_mfma_f32_16x16x32_bf16 v[38:41], v[146:149], v[170:173], v[38:41]
	v_mfma_f32_16x16x32_bf16 v[38:41], v[150:153], v[174:177], v[38:41]
	v_mfma_f32_16x16x32_bf16 v[34:37], v[154:157], v[170:173], v[34:37]
	v_mfma_f32_16x16x32_bf16 v[34:37], v[158:161], v[174:177], v[34:37]
	v_mfma_f32_16x16x32_bf16 v[22:25], v[146:149], v[186:189], v[22:25]
	v_mfma_f32_16x16x32_bf16 v[22:25], v[150:153], v[190:193], v[22:25]
	v_mfma_f32_16x16x32_bf16 v[18:21], v[154:157], v[186:189], v[18:21]
	v_mfma_f32_16x16x32_bf16 v[18:21], v[158:161], v[190:193], v[18:21]
	v_mfma_f32_16x16x32_bf16 v[6:9], v[146:149], v[194:197], v[6:9]
	v_mfma_f32_16x16x32_bf16 v[6:9], v[150:153], v[204:207], v[6:9]
	v_mfma_f32_16x16x32_bf16 v[2:5], v[154:157], v[194:197], v[2:5]
	v_mfma_f32_16x16x32_bf16 v[2:5], v[158:161], v[204:207], v[2:5]
	s_barrier
	s_add_i32 s55, s55, 2
	s_add_i32 s56, s56, 0x10000
	s_cmpk_gt_u32 s55, 0x7d
	s_mov_b64 s[36:37], s[38:39]
	s_cbranch_scc0 .LBB0_519
	s_and_b64 vcc, exec, s[18:19]
	s_cbranch_vccz .LBB0_522
	s_barrier

.LBB0_612:
	ds_read_b128 v[166:169], v152
	ds_read_b128 v[170:173], v152 offset:1024
	ds_read_b128 v[174:177], v152 offset:2048
	ds_read_b128 v[178:181], v152 offset:3072
	ds_read_b128 v[182:185], v153
	ds_read_b128 v[186:189], v153 offset:1024
	ds_read_b128 v[190:193], v153 offset:2048
	ds_read_b128 v[194:197], v153 offset:3072
	s_add_u32 s26, s4, s22
	s_addc_u32 s27, s5, s23
	s_add_u32 s30, s26, 0x100
	s_addc_u32 s31, s27, 0
	s_add_u32 s28, s52, s22
	s_addc_u32 s29, s53, s23
	s_add_u32 s26, s26, 0x180
	s_addc_u32 s27, s27, 0
	s_cmpk_eq_i32 s22, 0x1f00
	s_cselect_b32 s27, s51, s27
	s_cselect_b32 s26, s50, s26
	s_cselect_b32 s29, s21, s29
	s_cselect_b32 s28, s20, s28
	s_cselect_b32 s31, s19, s31
	s_cselect_b32 s30, s18, s30
	s_mov_b32 m0, s37
	v_lshl_add_u64 v[210:211], v[148:149], 0, s[22:23]
	ds_read_b128 v[198:201], v154
	ds_read_b128 v[202:205], v154 offset:1024
	ds_read_b128 v[206:209], v154 offset:2048
	ds_read_b128 v[214:217], v154 offset:3072
	ds_read_b128 v[218:221], v154 offset:4096
	ds_read_b128 v[222:225], v154 offset:5120
	ds_read_b128 v[226:229], v154 offset:6144
	ds_read_b128 v[230:233], v154 offset:7168
	global_load_lds_dwordx4 v[210:211], off
	v_lshl_add_u64 v[210:211], v[150:151], 0, s[22:23]
	s_mov_b32 m0, s38
	s_nop 0
	global_load_lds_dwordx4 v[210:211], off
	s_waitcnt vmcnt(8)
	s_waitcnt lgkmcnt(0)
	s_barrier
	s_waitcnt lgkmcnt(0)
	v_mfma_f32_16x16x32_bf16 v[126:129], v[166:169], v[198:201], v[126:129]
	v_mfma_f32_16x16x32_bf16 v[126:129], v[170:173], v[202:205], v[126:129]
	v_mfma_f32_16x16x32_bf16 v[122:125], v[174:177], v[198:201], v[122:125]
	v_mfma_f32_16x16x32_bf16 v[122:125], v[178:181], v[202:205], v[122:125]
	v_mfma_f32_16x16x32_bf16 v[110:113], v[166:169], v[206:209], v[110:113]
	v_mfma_f32_16x16x32_bf16 v[110:113], v[170:173], v[214:217], v[110:113]
	v_mfma_f32_16x16x32_bf16 v[106:109], v[174:177], v[206:209], v[106:109]
	v_mfma_f32_16x16x32_bf16 v[106:109], v[178:181], v[214:217], v[106:109]
	v_mfma_f32_16x16x32_bf16 v[94:97], v[166:169], v[218:221], v[94:97]
	v_mfma_f32_16x16x32_bf16 v[94:97], v[170:173], v[222:225], v[94:97]
	v_mfma_f32_16x16x32_bf16 v[90:93], v[174:177], v[218:221], v[90:93]
	v_mfma_f32_16x16x32_bf16 v[90:93], v[178:181], v[222:225], v[90:93]
	v_mfma_f32_16x16x32_bf16 v[78:81], v[166:169], v[226:229], v[78:81]
	v_mfma_f32_16x16x32_bf16 v[78:81], v[170:173], v[230:233], v[78:81]
	v_mfma_f32_16x16x32_bf16 v[74:77], v[174:177], v[226:229], v[74:77]
	v_mfma_f32_16x16x32_bf16 v[74:77], v[178:181], v[230:233], v[74:77]
	v_mfma_f32_16x16x32_bf16 v[118:121], v[182:185], v[198:201], v[118:121]
	v_mfma_f32_16x16x32_bf16 v[118:121], v[186:189], v[202:205], v[118:121]
	v_mfma_f32_16x16x32_bf16 v[114:117], v[190:193], v[198:201], v[114:117]
	v_mfma_f32_16x16x32_bf16 v[114:117], v[194:197], v[202:205], v[114:117]
	v_mfma_f32_16x16x32_bf16 v[102:105], v[182:185], v[206:209], v[102:105]
	v_mfma_f32_16x16x32_bf16 v[102:105], v[186:189], v[214:217], v[102:105]
	v_mfma_f32_16x16x32_bf16 v[98:101], v[190:193], v[206:209], v[98:101]
	v_mfma_f32_16x16x32_bf16 v[98:101], v[194:197], v[214:217], v[98:101]
	v_mfma_f32_16x16x32_bf16 v[86:89], v[182:185], v[218:221], v[86:89]
	v_mfma_f32_16x16x32_bf16 v[86:89], v[186:189], v[222:225], v[86:89]
	v_mfma_f32_16x16x32_bf16 v[82:85], v[190:193], v[218:221], v[82:85]
	v_mfma_f32_16x16x32_bf16 v[82:85], v[194:197], v[222:225], v[82:85]
	v_mfma_f32_16x16x32_bf16 v[70:73], v[182:185], v[226:229], v[70:73]
	v_mfma_f32_16x16x32_bf16 v[70:73], v[186:189], v[230:233], v[70:73]
	v_mfma_f32_16x16x32_bf16 v[66:69], v[190:193], v[226:229], v[66:69]
	v_mfma_f32_16x16x32_bf16 v[66:69], v[194:197], v[230:233], v[66:69]
	s_barrier
	s_mov_b32 m0, s39
	v_lshl_add_u64 v[210:211], s[28:29], 0, v[132:133]
	s_add_u32 s56, s28, 0x108000
	ds_read_b128 v[198:201], v154 offset:16384
	ds_read_b128 v[202:205], v154 offset:17408
	ds_read_b128 v[206:209], v154 offset:18432
	ds_read_b128 v[214:217], v154 offset:19456
	ds_read_b128 v[218:221], v154 offset:20480
	ds_read_b128 v[222:225], v154 offset:21504
	ds_read_b128 v[226:229], v154 offset:22528
	ds_read_b128 v[230:233], v154 offset:23552
	global_load_lds_dwordx4 v[210:211], off
	v_lshl_add_u64 v[234:235], s[28:29], 0, v[136:137]
	s_mov_b32 m0, s40
	s_addc_u32 s57, s29, 0
	global_load_lds_dwordx4 v[234:235], off
	v_lshl_add_u64 v[236:237], s[56:57], 0, v[132:133]
	s_mov_b32 m0, s41
	s_nop 0
	global_load_lds_dwordx4 v[236:237], off
	v_lshl_add_u64 v[236:237], s[56:57], 0, v[136:137]
	s_mov_b32 m0, s42
	s_nop 0
	global_load_lds_dwordx4 v[236:237], off
	v_lshl_add_u64 v[236:237], s[30:31], 0, v[130:131]
	s_mov_b32 m0, s2
	s_nop 0
	global_load_lds_dwordx4 v[236:237], off
	v_lshl_add_u64 v[236:237], s[30:31], 0, v[134:135]
	s_mov_b32 m0, s3
	s_nop 0
	global_load_lds_dwordx4 v[236:237], off
	s_waitcnt vmcnt(8)
	s_waitcnt lgkmcnt(0)
	s_barrier
	s_waitcnt lgkmcnt(0)
	v_mfma_f32_16x16x32_bf16 v[62:65], v[166:169], v[198:201], v[62:65]
	v_mfma_f32_16x16x32_bf16 v[62:65], v[170:173], v[202:205], v[62:65]
	v_mfma_f32_16x16x32_bf16 v[58:61], v[174:177], v[198:201], v[58:61]
	v_mfma_f32_16x16x32_bf16 v[58:61], v[178:181], v[202:205], v[58:61]
	v_mfma_f32_16x16x32_bf16 v[46:49], v[166:169], v[206:209], v[46:49]
	v_mfma_f32_16x16x32_bf16 v[46:49], v[170:173], v[214:217], v[46:49]
	v_mfma_f32_16x16x32_bf16 v[42:45], v[174:177], v[206:209], v[42:45]
	v_mfma_f32_16x16x32_bf16 v[42:45], v[178:181], v[214:217], v[42:45]
	v_mfma_f32_16x16x32_bf16 v[30:33], v[166:169], v[218:221], v[30:33]
	v_mfma_f32_16x16x32_bf16 v[30:33], v[170:173], v[222:225], v[30:33]
	v_mfma_f32_16x16x32_bf16 v[26:29], v[174:177], v[218:221], v[26:29]
	v_mfma_f32_16x16x32_bf16 v[26:29], v[178:181], v[222:225], v[26:29]
	v_mfma_f32_16x16x32_bf16 v[14:17], v[166:169], v[226:229], v[14:17]
	v_mfma_f32_16x16x32_bf16 v[14:17], v[170:173], v[230:233], v[14:17]
	v_mfma_f32_16x16x32_bf16 v[10:13], v[174:177], v[226:229], v[10:13]
	v_mfma_f32_16x16x32_bf16 v[10:13], v[178:181], v[230:233], v[10:13]
	v_mfma_f32_16x16x32_bf16 v[54:57], v[182:185], v[198:201], v[54:57]
	v_mfma_f32_16x16x32_bf16 v[54:57], v[186:189], v[202:205], v[54:57]
	v_mfma_f32_16x16x32_bf16 v[50:53], v[190:193], v[198:201], v[50:53]
	v_mfma_f32_16x16x32_bf16 v[50:53], v[194:197], v[202:205], v[50:53]
	v_mfma_f32_16x16x32_bf16 v[38:41], v[182:185], v[206:209], v[38:41]
	v_mfma_f32_16x16x32_bf16 v[38:41], v[186:189], v[214:217], v[38:41]
	v_mfma_f32_16x16x32_bf16 v[34:37], v[190:193], v[206:209], v[34:37]
	v_mfma_f32_16x16x32_bf16 v[34:37], v[194:197], v[214:217], v[34:37]
	v_mfma_f32_16x16x32_bf16 v[22:25], v[182:185], v[218:221], v[22:25]
	v_mfma_f32_16x16x32_bf16 v[22:25], v[186:189], v[222:225], v[22:25]
	v_mfma_f32_16x16x32_bf16 v[18:21], v[190:193], v[218:221], v[18:21]
	v_mfma_f32_16x16x32_bf16 v[18:21], v[194:197], v[222:225], v[18:21]
	v_mfma_f32_16x16x32_bf16 v[6:9], v[182:185], v[226:229], v[6:9]
	v_mfma_f32_16x16x32_bf16 v[6:9], v[186:189], v[230:233], v[6:9]
	v_mfma_f32_16x16x32_bf16 v[2:5], v[190:193], v[226:229], v[2:5]
	v_mfma_f32_16x16x32_bf16 v[2:5], v[194:197], v[230:233], v[2:5]
	s_barrier
	ds_read_b128 v[166:169], v156
	ds_read_b128 v[170:173], v156 offset:1024
	ds_read_b128 v[174:177], v156 offset:2048
	ds_read_b128 v[178:181], v156 offset:3072
	ds_read_b128 v[182:185], v157
	ds_read_b128 v[186:189], v157 offset:1024
	ds_read_b128 v[190:193], v157 offset:2048
	ds_read_b128 v[194:197], v157 offset:3072
	s_add_u32 s30, s30, 0x108000
	s_addc_u32 s31, s31, 0
	s_mov_b32 m0, s33
	v_lshl_add_u64 v[236:237], s[30:31], 0, v[130:131]
	ds_read_b128 v[198:201], v154 offset:32768
	ds_read_b128 v[202:205], v154 offset:33792
	ds_read_b128 v[206:209], v154 offset:34816
	ds_read_b128 v[214:217], v154 offset:35840
	ds_read_b128 v[218:221], v154 offset:36864
	ds_read_b128 v[222:225], v154 offset:37888
	ds_read_b128 v[226:229], v154 offset:38912
	ds_read_b128 v[230:233], v154 offset:39936
	global_load_lds_dwordx4 v[236:237], off
	v_lshl_add_u64 v[236:237], s[30:31], 0, v[134:135]
	s_mov_b32 m0, s34
	s_nop 0
	global_load_lds_dwordx4 v[236:237], off
	s_waitcnt vmcnt(8)
	s_waitcnt lgkmcnt(0)
	s_barrier
	s_waitcnt lgkmcnt(0)
	v_mfma_f32_16x16x32_bf16 v[126:129], v[166:169], v[198:201], v[126:129]
	v_mfma_f32_16x16x32_bf16 v[126:129], v[170:173], v[202:205], v[126:129]
	v_mfma_f32_16x16x32_bf16 v[122:125], v[174:177], v[198:201], v[122:125]
	v_mfma_f32_16x16x32_bf16 v[122:125], v[178:181], v[202:205], v[122:125]
	v_mfma_f32_16x16x32_bf16 v[110:113], v[166:169], v[206:209], v[110:113]
	v_mfma_f32_16x16x32_bf16 v[110:113], v[170:173], v[214:217], v[110:113]
	v_mfma_f32_16x16x32_bf16 v[106:109], v[174:177], v[206:209], v[106:109]
	v_mfma_f32_16x16x32_bf16 v[106:109], v[178:181], v[214:217], v[106:109]
	v_mfma_f32_16x16x32_bf16 v[94:97], v[166:169], v[218:221], v[94:97]
	v_mfma_f32_16x16x32_bf16 v[94:97], v[170:173], v[222:225], v[94:97]
	v_mfma_f32_16x16x32_bf16 v[90:93], v[174:177], v[218:221], v[90:93]
	v_mfma_f32_16x16x32_bf16 v[90:93], v[178:181], v[222:225], v[90:93]
	v_mfma_f32_16x16x32_bf16 v[78:81], v[166:169], v[226:229], v[78:81]
	v_mfma_f32_16x16x32_bf16 v[78:81], v[170:173], v[230:233], v[78:81]
	v_mfma_f32_16x16x32_bf16 v[74:77], v[174:177], v[226:229], v[74:77]
	v_mfma_f32_16x16x32_bf16 v[74:77], v[178:181], v[230:233], v[74:77]
	v_mfma_f32_16x16x32_bf16 v[118:121], v[182:185], v[198:201], v[118:121]
	v_mfma_f32_16x16x32_bf16 v[118:121], v[186:189], v[202:205], v[118:121]
	v_mfma_f32_16x16x32_bf16 v[114:117], v[190:193], v[198:201], v[114:117]
	v_mfma_f32_16x16x32_bf16 v[114:117], v[194:197], v[202:205], v[114:117]
	v_mfma_f32_16x16x32_bf16 v[102:105], v[182:185], v[206:209], v[102:105]
	v_mfma_f32_16x16x32_bf16 v[102:105], v[186:189], v[214:217], v[102:105]
	v_mfma_f32_16x16x32_bf16 v[98:101], v[190:193], v[206:209], v[98:101]
	v_mfma_f32_16x16x32_bf16 v[98:101], v[194:197], v[214:217], v[98:101]
	v_mfma_f32_16x16x32_bf16 v[86:89], v[182:185], v[218:221], v[86:89]
	v_mfma_f32_16x16x32_bf16 v[86:89], v[186:189], v[222:225], v[86:89]
	v_mfma_f32_16x16x32_bf16 v[82:85], v[190:193], v[218:221], v[82:85]
	v_mfma_f32_16x16x32_bf16 v[82:85], v[194:197], v[222:225], v[82:85]
	v_mfma_f32_16x16x32_bf16 v[70:73], v[182:185], v[226:229], v[70:73]
	v_mfma_f32_16x16x32_bf16 v[70:73], v[186:189], v[230:233], v[70:73]
	v_mfma_f32_16x16x32_bf16 v[66:69], v[190:193], v[226:229], v[66:69]
	v_mfma_f32_16x16x32_bf16 v[66:69], v[194:197], v[230:233], v[66:69]
	s_barrier
	s_mov_b32 m0, s43
	v_lshl_add_u64 v[210:211], v[210:211], 0, s[14:15]
	s_add_u32 s28, s28, 0x108080
	ds_read_b128 v[198:201], v154 offset:49152
	ds_read_b128 v[202:205], v154 offset:50176
	ds_read_b128 v[206:209], v154 offset:51200
	ds_read_b128 v[214:217], v154 offset:52224
	ds_read_b128 v[218:221], v154 offset:53248
	ds_read_b128 v[222:225], v154 offset:54272
	ds_read_b128 v[226:229], v154 offset:55296
	ds_read_b128 v[230:233], v154 offset:56320
	global_load_lds_dwordx4 v[210:211], off
	v_lshl_add_u64 v[210:211], v[234:235], 0, s[14:15]
	s_mov_b32 m0, s44
	s_addc_u32 s29, s29, 0
	global_load_lds_dwordx4 v[210:211], off
	v_lshl_add_u64 v[210:211], s[28:29], 0, v[132:133]
	s_mov_b32 m0, s45
	s_nop 0
	global_load_lds_dwordx4 v[210:211], off
	v_lshl_add_u64 v[210:211], s[28:29], 0, v[136:137]
	s_mov_b32 m0, s46
	s_nop 0
	global_load_lds_dwordx4 v[210:211], off
	v_lshl_add_u64 v[210:211], s[26:27], 0, v[130:131]
	s_mov_b32 m0, s35
	s_nop 0
	global_load_lds_dwordx4 v[210:211], off
	v_lshl_add_u64 v[210:211], s[26:27], 0, v[134:135]
	s_mov_b32 m0, s36
	s_nop 0
	global_load_lds_dwordx4 v[210:211], off
	s_waitcnt vmcnt(8)
	s_waitcnt lgkmcnt(0)
	s_barrier
	s_waitcnt lgkmcnt(0)
	v_mfma_f32_16x16x32_bf16 v[62:65], v[166:169], v[198:201], v[62:65]
	v_mfma_f32_16x16x32_bf16 v[62:65], v[170:173], v[202:205], v[62:65]
	v_mfma_f32_16x16x32_bf16 v[58:61], v[174:177], v[198:201], v[58:61]
	v_mfma_f32_16x16x32_bf16 v[58:61], v[178:181], v[202:205], v[58:61]
	v_mfma_f32_16x16x32_bf16 v[46:49], v[166:169], v[206:209], v[46:49]
	v_mfma_f32_16x16x32_bf16 v[46:49], v[170:173], v[214:217], v[46:49]
	v_mfma_f32_16x16x32_bf16 v[42:45], v[174:177], v[206:209], v[42:45]
	v_mfma_f32_16x16x32_bf16 v[42:45], v[178:181], v[214:217], v[42:45]
	v_mfma_f32_16x16x32_bf16 v[30:33], v[166:169], v[218:221], v[30:33]
	v_mfma_f32_16x16x32_bf16 v[30:33], v[170:173], v[222:225], v[30:33]
	v_mfma_f32_16x16x32_bf16 v[26:29], v[174:177], v[218:221], v[26:29]
	v_mfma_f32_16x16x32_bf16 v[26:29], v[178:181], v[222:225], v[26:29]
	v_mfma_f32_16x16x32_bf16 v[14:17], v[166:169], v[226:229], v[14:17]
	v_mfma_f32_16x16x32_bf16 v[14:17], v[170:173], v[230:233], v[14:17]
	v_mfma_f32_16x16x32_bf16 v[10:13], v[174:177], v[226:229], v[10:13]
	v_mfma_f32_16x16x32_bf16 v[10:13], v[178:181], v[230:233], v[10:13]
	v_mfma_f32_16x16x32_bf16 v[54:57], v[182:185], v[198:201], v[54:57]
	v_mfma_f32_16x16x32_bf16 v[54:57], v[186:189], v[202:205], v[54:57]
	v_mfma_f32_16x16x32_bf16 v[50:53], v[190:193], v[198:201], v[50:53]
	v_mfma_f32_16x16x32_bf16 v[50:53], v[194:197], v[202:205], v[50:53]
	v_mfma_f32_16x16x32_bf16 v[38:41], v[182:185], v[206:209], v[38:41]
	v_mfma_f32_16x16x32_bf16 v[38:41], v[186:189], v[214:217], v[38:41]
	v_mfma_f32_16x16x32_bf16 v[34:37], v[190:193], v[206:209], v[34:37]
	v_mfma_f32_16x16x32_bf16 v[34:37], v[194:197], v[214:217], v[34:37]
	v_mfma_f32_16x16x32_bf16 v[22:25], v[182:185], v[218:221], v[22:25]
	v_mfma_f32_16x16x32_bf16 v[22:25], v[186:189], v[222:225], v[22:25]
	v_mfma_f32_16x16x32_bf16 v[18:21], v[190:193], v[218:221], v[18:21]
	v_mfma_f32_16x16x32_bf16 v[18:21], v[194:197], v[222:225], v[18:21]
	v_mfma_f32_16x16x32_bf16 v[6:9], v[182:185], v[226:229], v[6:9]
	v_mfma_f32_16x16x32_bf16 v[6:9], v[186:189], v[230:233], v[6:9]
	v_mfma_f32_16x16x32_bf16 v[2:5], v[190:193], v[226:229], v[2:5]
	v_mfma_f32_16x16x32_bf16 v[2:5], v[194:197], v[230:233], v[2:5]
	s_barrier
	s_add_i32 s54, s54, 2
	s_add_u32 s22, s22, 0x100
	s_addc_u32 s23, s23, 0
	s_cmp_gt_u32 s54, 61
	s_cbranch_scc0 .LBB0_612
	s_and_b64 vcc, exec, s[16:17]
	s_cbranch_vccz .LBB0_615
	s_barrier

.LBB0_844:
	s_add_i32 s35, s52, 0xfffe8000
	s_and_b32 s34, s30, 0x100
	s_and_b32 s35, s35, 0x3e0000
	s_or_b32 s34, s34, s35
	s_add_u32 s53, s28, s34
	s_addc_u32 s55, s29, 0
	s_add_u32 s34, s30, 0x100
	s_addc_u32 s35, s31, 0
	s_add_i32 s37, s52, 0xffff8000
	s_and_b32 s36, s34, 0x100
	s_and_b32 s37, s37, 0x7e0000
	s_or_b32 s36, s37, s36
	s_add_u32 s36, s28, s36
	s_addc_u32 s37, s29, 0
	s_add_u32 s54, s49, s30
	s_addc_u32 s31, s50, s31
	s_add_i32 s38, s30, 0x180
	s_and_b32 s38, s38, 0x180
	s_and_b32 s39, s52, 0x7e0000
	s_or_b32 s38, s39, s38
	s_add_u32 s56, s28, s38
	s_addc_u32 s57, s29, 0
	s_cmpk_eq_i32 s30, 0x3f00
	s_cselect_b32 s39, s1, s37
	s_cselect_b32 s38, s21, s36
	s_cselect_b32 s37, s23, s31
	s_cselect_b32 s36, s22, s54
	s_cselect_b32 s31, s48, s57
	s_cselect_b32 s30, s27, s56
	s_add_i32 s56, 0, 0x10000
	v_add_u32_e32 v124, s56, v211
	ds_read_b128 v[104:107], v124
	ds_read_b128 v[108:111], v124 offset:1024
	ds_read_b128 v[120:123], v124 offset:2048
	ds_read_b128 v[124:127], v124 offset:3072
	ds_read_b128 v[144:147], v214
	ds_read_b128 v[148:151], v214 offset:1024
	ds_read_b128 v[152:155], v214 offset:2048
	ds_read_b128 v[156:159], v214 offset:3072
	s_add_u32 s54, s53, 0x10080
	s_addc_u32 s55, s55, 0
	v_lshl_add_u64 v[200:201], s[54:55], 0, v[184:185]
	s_add_i32 m0, s3, 0xc000
	ds_read_b128 v[160:163], v215
	ds_read_b128 v[164:167], v215 offset:1024
	ds_read_b128 v[168:171], v215 offset:2048
	ds_read_b128 v[172:175], v215 offset:3072
	ds_read_b128 v[176:179], v215 offset:4096
	ds_read_b128 v[180:183], v215 offset:5120
	ds_read_b128 v[192:195], v215 offset:6144
	ds_read_b128 v[196:199], v215 offset:7168
	global_load_lds_dwordx4 v[200:201], off
	v_lshl_add_u64 v[200:201], s[54:55], 0, v[188:189]
	s_add_i32 m0, s3, 0xe000
	s_nop 0
	global_load_lds_dwordx4 v[200:201], off
	s_waitcnt vmcnt(8)
	s_waitcnt lgkmcnt(0)
	s_barrier
	s_waitcnt lgkmcnt(0)
	v_mfma_f32_16x16x32_bf16 v[140:143], v[104:107], v[160:163], v[140:143]
	v_mfma_f32_16x16x32_bf16 v[140:143], v[108:111], v[164:167], v[140:143]
	v_mfma_f32_16x16x32_bf16 v[136:139], v[120:123], v[160:163], v[136:139]
	v_mfma_f32_16x16x32_bf16 v[136:139], v[124:127], v[164:167], v[136:139]
	v_mfma_f32_16x16x32_bf16 v[116:119], v[104:107], v[168:171], v[116:119]
	v_mfma_f32_16x16x32_bf16 v[116:119], v[108:111], v[172:175], v[116:119]
	v_mfma_f32_16x16x32_bf16 v[112:115], v[120:123], v[168:171], v[112:115]
	v_mfma_f32_16x16x32_bf16 v[112:115], v[124:127], v[172:175], v[112:115]
	v_mfma_f32_16x16x32_bf16 v[92:95], v[104:107], v[176:179], v[92:95]
	v_mfma_f32_16x16x32_bf16 v[92:95], v[108:111], v[180:183], v[92:95]
	v_mfma_f32_16x16x32_bf16 v[88:91], v[120:123], v[176:179], v[88:91]
	v_mfma_f32_16x16x32_bf16 v[88:91], v[124:127], v[180:183], v[88:91]
	v_mfma_f32_16x16x32_bf16 v[76:79], v[104:107], v[192:195], v[76:79]
	v_mfma_f32_16x16x32_bf16 v[76:79], v[108:111], v[196:199], v[76:79]
	v_mfma_f32_16x16x32_bf16 v[72:75], v[120:123], v[192:195], v[72:75]
	v_mfma_f32_16x16x32_bf16 v[72:75], v[124:127], v[196:199], v[72:75]
	v_mfma_f32_16x16x32_bf16 v[132:135], v[144:147], v[160:163], v[132:135]
	v_mfma_f32_16x16x32_bf16 v[132:135], v[148:151], v[164:167], v[132:135]
	v_mfma_f32_16x16x32_bf16 v[128:131], v[152:155], v[160:163], v[128:131]
	v_mfma_f32_16x16x32_bf16 v[128:131], v[156:159], v[164:167], v[128:131]
	v_mfma_f32_16x16x32_bf16 v[100:103], v[144:147], v[168:171], v[100:103]
	v_mfma_f32_16x16x32_bf16 v[100:103], v[148:151], v[172:175], v[100:103]
	v_mfma_f32_16x16x32_bf16 v[96:99], v[152:155], v[168:171], v[96:99]
	v_mfma_f32_16x16x32_bf16 v[96:99], v[156:159], v[172:175], v[96:99]
	v_mfma_f32_16x16x32_bf16 v[84:87], v[144:147], v[176:179], v[84:87]
	v_mfma_f32_16x16x32_bf16 v[84:87], v[148:151], v[180:183], v[84:87]
	v_mfma_f32_16x16x32_bf16 v[80:83], v[152:155], v[176:179], v[80:83]
	v_mfma_f32_16x16x32_bf16 v[80:83], v[156:159], v[180:183], v[80:83]
	v_mfma_f32_16x16x32_bf16 v[68:71], v[144:147], v[192:195], v[68:71]
	v_mfma_f32_16x16x32_bf16 v[68:71], v[148:151], v[196:199], v[68:71]
	v_mfma_f32_16x16x32_bf16 v[64:67], v[152:155], v[192:195], v[64:67]
	v_mfma_f32_16x16x32_bf16 v[64:67], v[156:159], v[196:199], v[64:67]
	s_barrier
	s_add_i32 s53, s56, s2
	v_lshl_add_u64 v[200:201], s[36:37], 0, v[186:187]
	s_mov_b32 m0, s53
	ds_read_b128 v[160:163], v215 offset:16384
	ds_read_b128 v[164:167], v215 offset:17408
	ds_read_b128 v[168:171], v215 offset:18432
	ds_read_b128 v[172:175], v215 offset:19456
	ds_read_b128 v[176:179], v215 offset:20480
	ds_read_b128 v[180:183], v215 offset:21504
	ds_read_b128 v[192:195], v215 offset:22528
	ds_read_b128 v[196:199], v215 offset:23552
	global_load_lds_dwordx4 v[200:201], off
	s_add_i32 m0, s53, 0x2000
	s_add_u32 s54, s36, 0x208000
	v_lshl_add_u64 v[202:203], s[36:37], 0, v[190:191]
	s_addc_u32 s55, s37, 0
	s_add_i32 s53, s45, s2
	global_load_lds_dwordx4 v[202:203], off
	v_lshl_add_u64 v[204:205], s[54:55], 0, v[186:187]
	s_mov_b32 m0, s53
	s_nop 0
	global_load_lds_dwordx4 v[204:205], off
	v_lshl_add_u64 v[204:205], s[54:55], 0, v[190:191]
	s_add_i32 m0, s53, 0x2000
	s_nop 0
	global_load_lds_dwordx4 v[204:205], off
	v_lshl_add_u64 v[204:205], s[38:39], 0, v[184:185]
	s_mov_b32 m0, s3
	s_nop 0
	global_load_lds_dwordx4 v[204:205], off
	v_lshl_add_u64 v[204:205], s[38:39], 0, v[188:189]
	s_mov_b32 m0, s33
	s_nop 0
	global_load_lds_dwordx4 v[204:205], off
	s_waitcnt vmcnt(8)
	s_waitcnt lgkmcnt(0)
	s_barrier
	s_waitcnt lgkmcnt(0)
	v_mfma_f32_16x16x32_bf16 v[60:63], v[104:107], v[160:163], v[60:63]
	v_mfma_f32_16x16x32_bf16 v[60:63], v[108:111], v[164:167], v[60:63]
	v_mfma_f32_16x16x32_bf16 v[56:59], v[120:123], v[160:163], v[56:59]
	v_mfma_f32_16x16x32_bf16 v[56:59], v[124:127], v[164:167], v[56:59]
	v_mfma_f32_16x16x32_bf16 v[44:47], v[104:107], v[168:171], v[44:47]
	v_mfma_f32_16x16x32_bf16 v[44:47], v[108:111], v[172:175], v[44:47]
	v_mfma_f32_16x16x32_bf16 v[40:43], v[120:123], v[168:171], v[40:43]
	v_mfma_f32_16x16x32_bf16 v[40:43], v[124:127], v[172:175], v[40:43]
	v_mfma_f32_16x16x32_bf16 v[28:31], v[104:107], v[176:179], v[28:31]
	v_mfma_f32_16x16x32_bf16 v[28:31], v[108:111], v[180:183], v[28:31]
	v_mfma_f32_16x16x32_bf16 v[24:27], v[120:123], v[176:179], v[24:27]
	v_mfma_f32_16x16x32_bf16 v[24:27], v[124:127], v[180:183], v[24:27]
	v_mfma_f32_16x16x32_bf16 v[12:15], v[104:107], v[192:195], v[12:15]
	v_mfma_f32_16x16x32_bf16 v[12:15], v[108:111], v[196:199], v[12:15]
	v_mfma_f32_16x16x32_bf16 v[8:11], v[120:123], v[192:195], v[8:11]
	v_mfma_f32_16x16x32_bf16 v[8:11], v[124:127], v[196:199], v[8:11]
	v_mfma_f32_16x16x32_bf16 v[52:55], v[144:147], v[160:163], v[52:55]
	v_mfma_f32_16x16x32_bf16 v[52:55], v[148:151], v[164:167], v[52:55]
	v_mfma_f32_16x16x32_bf16 v[48:51], v[152:155], v[160:163], v[48:51]
	v_mfma_f32_16x16x32_bf16 v[48:51], v[156:159], v[164:167], v[48:51]
	v_mfma_f32_16x16x32_bf16 v[36:39], v[144:147], v[168:171], v[36:39]
	v_mfma_f32_16x16x32_bf16 v[36:39], v[148:151], v[172:175], v[36:39]
	v_mfma_f32_16x16x32_bf16 v[32:35], v[152:155], v[168:171], v[32:35]
	v_mfma_f32_16x16x32_bf16 v[32:35], v[156:159], v[172:175], v[32:35]
	v_mfma_f32_16x16x32_bf16 v[20:23], v[144:147], v[176:179], v[20:23]
	v_mfma_f32_16x16x32_bf16 v[20:23], v[148:151], v[180:183], v[20:23]
	v_mfma_f32_16x16x32_bf16 v[16:19], v[152:155], v[176:179], v[16:19]
	v_mfma_f32_16x16x32_bf16 v[16:19], v[156:159], v[180:183], v[16:19]
	v_mfma_f32_16x16x32_bf16 v[4:7], v[144:147], v[192:195], v[4:7]
	v_mfma_f32_16x16x32_bf16 v[4:7], v[148:151], v[196:199], v[4:7]
	v_mfma_f32_16x16x32_bf16 v[0:3], v[152:155], v[192:195], v[0:3]
	v_mfma_f32_16x16x32_bf16 v[0:3], v[156:159], v[196:199], v[0:3]
	s_barrier
	s_add_i32 s53, 0, 0x18000
	s_add_i32 s54, 0, 0x1c000
	v_add_u32_e32 v124, s53, v211
	v_add_u32_e32 v156, s54, v211
	ds_read_b128 v[104:107], v124
	ds_read_b128 v[108:111], v124 offset:1024
	ds_read_b128 v[120:123], v124 offset:2048
	ds_read_b128 v[124:127], v124 offset:3072
	ds_read_b128 v[144:147], v156
	ds_read_b128 v[148:151], v156 offset:1024
	ds_read_b128 v[152:155], v156 offset:2048
	ds_read_b128 v[156:159], v156 offset:3072
	s_add_u32 s38, s38, 0x10000
	s_addc_u32 s39, s39, 0
	s_mov_b32 m0, s40
	v_lshl_add_u64 v[204:205], s[38:39], 0, v[184:185]
	ds_read_b128 v[160:163], v215 offset:32768
	ds_read_b128 v[164:167], v215 offset:33792
	ds_read_b128 v[168:171], v215 offset:34816
	ds_read_b128 v[172:175], v215 offset:35840
	ds_read_b128 v[176:179], v215 offset:36864
	ds_read_b128 v[180:183], v215 offset:37888
	ds_read_b128 v[192:195], v215 offset:38912
	ds_read_b128 v[196:199], v215 offset:39936
	global_load_lds_dwordx4 v[204:205], off
	v_lshl_add_u64 v[204:205], s[38:39], 0, v[188:189]
	s_mov_b32 m0, s41
	s_nop 0
	global_load_lds_dwordx4 v[204:205], off
	s_waitcnt vmcnt(8)
	s_waitcnt lgkmcnt(0)
	s_barrier
	s_waitcnt lgkmcnt(0)
	v_mfma_f32_16x16x32_bf16 v[140:143], v[104:107], v[160:163], v[140:143]
	v_mfma_f32_16x16x32_bf16 v[140:143], v[108:111], v[164:167], v[140:143]
	v_mfma_f32_16x16x32_bf16 v[136:139], v[120:123], v[160:163], v[136:139]
	v_mfma_f32_16x16x32_bf16 v[136:139], v[124:127], v[164:167], v[136:139]
	v_mfma_f32_16x16x32_bf16 v[116:119], v[104:107], v[168:171], v[116:119]
	v_mfma_f32_16x16x32_bf16 v[116:119], v[108:111], v[172:175], v[116:119]
	v_mfma_f32_16x16x32_bf16 v[112:115], v[120:123], v[168:171], v[112:115]
	v_mfma_f32_16x16x32_bf16 v[112:115], v[124:127], v[172:175], v[112:115]
	v_mfma_f32_16x16x32_bf16 v[92:95], v[104:107], v[176:179], v[92:95]
	v_mfma_f32_16x16x32_bf16 v[92:95], v[108:111], v[180:183], v[92:95]
	v_mfma_f32_16x16x32_bf16 v[88:91], v[120:123], v[176:179], v[88:91]
	v_mfma_f32_16x16x32_bf16 v[88:91], v[124:127], v[180:183], v[88:91]
	v_mfma_f32_16x16x32_bf16 v[76:79], v[104:107], v[192:195], v[76:79]
	v_mfma_f32_16x16x32_bf16 v[76:79], v[108:111], v[196:199], v[76:79]
	v_mfma_f32_16x16x32_bf16 v[72:75], v[120:123], v[192:195], v[72:75]
	v_mfma_f32_16x16x32_bf16 v[72:75], v[124:127], v[196:199], v[72:75]
	v_mfma_f32_16x16x32_bf16 v[132:135], v[144:147], v[160:163], v[132:135]
	v_mfma_f32_16x16x32_bf16 v[132:135], v[148:151], v[164:167], v[132:135]
	v_mfma_f32_16x16x32_bf16 v[128:131], v[152:155], v[160:163], v[128:131]
	v_mfma_f32_16x16x32_bf16 v[128:131], v[156:159], v[164:167], v[128:131]
	v_mfma_f32_16x16x32_bf16 v[100:103], v[144:147], v[168:171], v[100:103]
	v_mfma_f32_16x16x32_bf16 v[100:103], v[148:151], v[172:175], v[100:103]
	v_mfma_f32_16x16x32_bf16 v[96:99], v[152:155], v[168:171], v[96:99]
	v_mfma_f32_16x16x32_bf16 v[96:99], v[156:159], v[172:175], v[96:99]
	v_mfma_f32_16x16x32_bf16 v[84:87], v[144:147], v[176:179], v[84:87]
	v_mfma_f32_16x16x32_bf16 v[84:87], v[148:151], v[180:183], v[84:87]
	v_mfma_f32_16x16x32_bf16 v[80:83], v[152:155], v[176:179], v[80:83]
	v_mfma_f32_16x16x32_bf16 v[80:83], v[156:159], v[180:183], v[80:83]
	v_mfma_f32_16x16x32_bf16 v[68:71], v[144:147], v[192:195], v[68:71]
	v_mfma_f32_16x16x32_bf16 v[68:71], v[148:151], v[196:199], v[68:71]
	v_mfma_f32_16x16x32_bf16 v[64:67], v[152:155], v[192:195], v[64:67]
	v_mfma_f32_16x16x32_bf16 v[64:67], v[156:159], v[196:199], v[64:67]
	s_barrier
	s_add_i32 s38, s53, s2
	v_lshl_add_u64 v[200:201], v[200:201], 0, s[16:17]
	s_mov_b32 m0, s38
	ds_read_b128 v[160:163], v215 offset:49152
	ds_read_b128 v[164:167], v215 offset:50176
	ds_read_b128 v[168:171], v215 offset:51200
	ds_read_b128 v[172:175], v215 offset:52224
	ds_read_b128 v[176:179], v215 offset:53248
	ds_read_b128 v[180:183], v215 offset:54272
	ds_read_b128 v[192:195], v215 offset:55296
	ds_read_b128 v[196:199], v215 offset:56320
	global_load_lds_dwordx4 v[200:201], off
	s_add_i32 m0, s38, 0x2000
	s_add_u32 s36, s36, 0x208080
	v_lshl_add_u64 v[200:201], v[202:203], 0, s[16:17]
	s_addc_u32 s37, s37, 0
	s_add_i32 s38, s54, s2
	global_load_lds_dwordx4 v[200:201], off
	v_lshl_add_u64 v[200:201], s[36:37], 0, v[186:187]
	s_mov_b32 m0, s38
	s_nop 0
	global_load_lds_dwordx4 v[200:201], off
	v_lshl_add_u64 v[200:201], s[36:37], 0, v[190:191]
	s_add_i32 m0, s38, 0x2000
	s_nop 0
	global_load_lds_dwordx4 v[200:201], off
	v_lshl_add_u64 v[200:201], s[30:31], 0, v[184:185]
	s_mov_b32 m0, s43
	s_nop 0
	global_load_lds_dwordx4 v[200:201], off
	v_lshl_add_u64 v[200:201], s[30:31], 0, v[188:189]
	s_mov_b32 m0, s44
	s_nop 0
	global_load_lds_dwordx4 v[200:201], off
	s_waitcnt vmcnt(8)
	s_waitcnt lgkmcnt(0)
	s_barrier
	s_waitcnt lgkmcnt(0)
	v_mfma_f32_16x16x32_bf16 v[60:63], v[104:107], v[160:163], v[60:63]
	v_mfma_f32_16x16x32_bf16 v[60:63], v[108:111], v[164:167], v[60:63]
	v_mfma_f32_16x16x32_bf16 v[56:59], v[120:123], v[160:163], v[56:59]
	v_mfma_f32_16x16x32_bf16 v[56:59], v[124:127], v[164:167], v[56:59]
	v_mfma_f32_16x16x32_bf16 v[44:47], v[104:107], v[168:171], v[44:47]
	v_mfma_f32_16x16x32_bf16 v[44:47], v[108:111], v[172:175], v[44:47]
	v_mfma_f32_16x16x32_bf16 v[40:43], v[120:123], v[168:171], v[40:43]
	v_mfma_f32_16x16x32_bf16 v[40:43], v[124:127], v[172:175], v[40:43]
	v_mfma_f32_16x16x32_bf16 v[28:31], v[104:107], v[176:179], v[28:31]
	v_mfma_f32_16x16x32_bf16 v[28:31], v[108:111], v[180:183], v[28:31]
	v_mfma_f32_16x16x32_bf16 v[24:27], v[120:123], v[176:179], v[24:27]
	v_mfma_f32_16x16x32_bf16 v[24:27], v[124:127], v[180:183], v[24:27]
	v_mfma_f32_16x16x32_bf16 v[12:15], v[104:107], v[192:195], v[12:15]
	v_mfma_f32_16x16x32_bf16 v[12:15], v[108:111], v[196:199], v[12:15]
	v_mfma_f32_16x16x32_bf16 v[8:11], v[120:123], v[192:195], v[8:11]
	v_mfma_f32_16x16x32_bf16 v[8:11], v[124:127], v[196:199], v[8:11]
	v_mfma_f32_16x16x32_bf16 v[52:55], v[144:147], v[160:163], v[52:55]
	v_mfma_f32_16x16x32_bf16 v[52:55], v[148:151], v[164:167], v[52:55]
	v_mfma_f32_16x16x32_bf16 v[48:51], v[152:155], v[160:163], v[48:51]
	v_mfma_f32_16x16x32_bf16 v[48:51], v[156:159], v[164:167], v[48:51]
	v_mfma_f32_16x16x32_bf16 v[36:39], v[144:147], v[168:171], v[36:39]
	v_mfma_f32_16x16x32_bf16 v[36:39], v[148:151], v[172:175], v[36:39]
	v_mfma_f32_16x16x32_bf16 v[32:35], v[152:155], v[168:171], v[32:35]
	v_mfma_f32_16x16x32_bf16 v[32:35], v[156:159], v[172:175], v[32:35]
	v_mfma_f32_16x16x32_bf16 v[20:23], v[144:147], v[176:179], v[20:23]
	v_mfma_f32_16x16x32_bf16 v[20:23], v[148:151], v[180:183], v[20:23]
	v_mfma_f32_16x16x32_bf16 v[16:19], v[152:155], v[176:179], v[16:19]
	v_mfma_f32_16x16x32_bf16 v[16:19], v[156:159], v[180:183], v[16:19]
	v_mfma_f32_16x16x32_bf16 v[4:7], v[144:147], v[192:195], v[4:7]
	v_mfma_f32_16x16x32_bf16 v[4:7], v[148:151], v[196:199], v[4:7]
	v_mfma_f32_16x16x32_bf16 v[0:3], v[152:155], v[192:195], v[0:3]
	v_mfma_f32_16x16x32_bf16 v[0:3], v[156:159], v[196:199], v[0:3]
	s_barrier
	s_add_i32 s51, s51, 2
	s_add_i32 s52, s52, 0x10000
	s_cmpk_gt_u32 s51, 0x7d
	s_mov_b64 s[30:31], s[34:35]
	s_cbranch_scc0 .LBB0_844
	s_and_b64 vcc, exec, s[18:19]
	s_cbranch_vccz .LBB0_847
	s_barrier
